# on top of residual rewrite: attention-epilogue ZS loads, EpiKN row-scale loads, EpiQ rsq and rope-table loads hoisted above the epilogue stores (counted vmcnt instead of 8-24 full drains per tile)
# speedup vs baseline: 1.0124x; 1.0073x over previous
; #define LAS __attribute__((address_space(3)))
; __device__ __forceinline__ unsigned pk2(float lo, float hi) { f32x2 v = {lo, hi}; bf16x2_t b = __builtin_convertvector(v, bf16x2_t); return __builtin_bit_cast(unsigned, b); }
; #define LDS_WAIT() asm volatile("s_waitcnt lgkmcnt(0)" ::: "memory")
; template <int MODE> __device__ __forceinline__ void attn_unit(const Args& A, LAS unsigned char* lds, bf16x8 (&qf)[12], AttDma& D, int& bufi, int b, int h, int qb,
;                                                               bool hasn, int bn, int hn, int qbn, int tid, int wid, int lane) {
;     ...
;     const float inv = 1.0f / (lrun + shx<32>(lrun));
;     int lane_e = lane; asm volatile("" : "+v"(lane_e));
;     const int r32e = lane_e & 31, halfe = lane_e >> 5;
;     LAS unsigned char* stg = lds + wid * (32 * OST);
; #pragma unroll
;     for (int d = 0; d < 4; ++d)
; #pragma unroll
;         for (int g4 = 0; g4 < 4; ++g4) { const int dv = 32 * d + 8 * g4 + 4 * halfe;
;             u32x2 w; w.x = pk2(o[d][4 * g4 + 0] * inv, o[d][4 * g4 + 1] * inv); w.y = pk2(o[d][4 * g4 + 2] * inv, o[d][4 * g4 + 3] * inv);
;             *(LAS u32x2*)(stg + r32e * OST + dv * 2) = w; }
;     LDS_WAIT(); asm volatile("" ::: "memory");
; #pragma unroll
;     for (int k = 0; k < 8; ++k) { const int idx = lane_e + 64 * k, qq = idx >> 4, ch = idx & 15;
;         const u32x4 ov = *(const LAS u32x4*)(stg + qq * OST + ch * 16);
;         const size_t off = (size_t)(tq0 + wid * 32 + qq) * MLAW + h * DV + ch * 8;
;         const u32x4 zv = *(const u32x4*)(ZS + off);
;         u32x4 r;
;         r.x = pk2(bf_lo(ov.x) * bf_lo(zv.x), bf_hi(ov.x) * bf_hi(zv.x)); r.y = pk2(bf_lo(ov.y) * bf_lo(zv.y), bf_hi(ov.y) * bf_hi(zv.y));
;         r.z = pk2(bf_lo(ov.z) * bf_lo(zv.z), bf_hi(ov.z) * bf_hi(zv.z)); r.w = pk2(bf_lo(ov.w) * bf_lo(zv.w), bf_hi(ov.w) * bf_hi(zv.w));
;         *(u32x4*)(O + off) = r; }
.LBB0_57:
	v_mbcnt_lo_u32_b32 v0, -1, 0
	v_mbcnt_hi_u32_b32 v0, -1, v0
	s_lshl_b32 s3, s22, 12
	v_lshlrev_b32_e32 v0, 2, v0
	v_xor_b32_e32 v0, 0x80, v0
	ds_bpermute_b32 v0, v0, v213
	s_lshl_b32 s2, s23, 8
	s_add_i32 s3, s3, s7
	s_add_i32 s2, s3, s2
	s_lshl_b32 s3, s1, 7
	s_waitcnt lgkmcnt(0)
	v_add_f32_e32 v0, v213, v0
	v_div_scale_f32 v66, s[4:5], v0, v0, 1.0
	v_rcp_f32_e32 v67, v66
	s_cmp_eq_u32 s97, s6
	s_mov_b32 s22, s90
	s_mov_b32 s1, s0
	v_fma_f32 v68, -v66, v67, 1.0
	v_fmac_f32_e32 v67, v68, v67
	v_div_scale_f32 v68, vcc, 1.0, v0, 1.0
	v_mul_f32_e32 v69, v68, v67
	v_fma_f32 v70, -v66, v69, v68
	v_fmac_f32_e32 v69, v70, v67
	v_fma_f32 v66, -v66, v69, v68
	v_div_fmas_f32 v66, v66, v67, v69
	v_div_fixup_f32 v0, v66, v0, 1.0
	v_mov_b32_e32 v66, v194
	v_pk_mul_f32 v[50:51], v[50:51], v[0:1] op_sel_hi:[1,0]
	v_pk_mul_f32 v[52:53], v[52:53], v[0:1] op_sel_hi:[1,0]
	v_cvt_pk_bf16_f32 v50, v50, v51
	v_and_b32_e32 v67, 31, v66
	v_cvt_pk_bf16_f32 v51, v52, v53
	v_ashrrev_i32_e32 v52, 2, v66
	v_pk_mul_f32 v[18:19], v[18:19], v[0:1] op_sel_hi:[1,0]
	v_pk_mul_f32 v[20:21], v[20:21], v[0:1] op_sel_hi:[1,0]
	v_mul_u32_u24_e32 v67, 0x110, v67
	v_and_b32_e32 v52, -8, v52
	v_cvt_pk_bf16_f32 v18, v18, v19
	v_cvt_pk_bf16_f32 v19, v20, v21
	v_pk_mul_f32 v[20:21], v[22:23], v[0:1] op_sel_hi:[1,0]
	v_pk_mul_f32 v[22:23], v[24:25], v[0:1] op_sel_hi:[1,0]
	v_add3_u32 v67, s93, v67, v52
	v_cvt_pk_bf16_f32 v20, v20, v21
	v_cvt_pk_bf16_f32 v21, v22, v23
	v_pk_mul_f32 v[2:3], v[2:3], v[0:1] op_sel_hi:[1,0]
	v_pk_mul_f32 v[4:5], v[4:5], v[0:1] op_sel_hi:[1,0]
	ds_write2_b64 v67, v[18:19], v[20:21] offset0:8 offset1:10
	v_pk_mul_f32 v[18:19], v[26:27], v[0:1] op_sel_hi:[1,0]
	v_pk_mul_f32 v[20:21], v[28:29], v[0:1] op_sel_hi:[1,0]
	v_cvt_pk_bf16_f32 v2, v2, v3
	v_cvt_pk_bf16_f32 v3, v4, v5
	v_pk_mul_f32 v[4:5], v[6:7], v[0:1] op_sel_hi:[1,0]
	v_pk_mul_f32 v[6:7], v[8:9], v[0:1] op_sel_hi:[1,0]
	v_cvt_pk_bf16_f32 v18, v18, v19
	v_cvt_pk_bf16_f32 v19, v20, v21
	v_pk_mul_f32 v[20:21], v[30:31], v[0:1] op_sel_hi:[1,0]
	v_pk_mul_f32 v[22:23], v[32:33], v[0:1] op_sel_hi:[1,0]
	v_cvt_pk_bf16_f32 v4, v4, v5
	v_cvt_pk_bf16_f32 v5, v6, v7
	v_cvt_pk_bf16_f32 v20, v20, v21
	v_cvt_pk_bf16_f32 v21, v22, v23
	ds_write2_b64 v67, v[2:3], v[4:5] offset0:24 offset1:26
	v_pk_mul_f32 v[2:3], v[10:11], v[0:1] op_sel_hi:[1,0]
	v_pk_mul_f32 v[4:5], v[12:13], v[0:1] op_sel_hi:[1,0]
	ds_write2_b64 v67, v[18:19], v[20:21] offset0:12 offset1:14
	v_pk_mul_f32 v[18:19], v[34:35], v[0:1] op_sel_hi:[1,0]
	v_pk_mul_f32 v[20:21], v[36:37], v[0:1] op_sel_hi:[1,0]
	v_cvt_pk_bf16_f32 v2, v2, v3
	v_cvt_pk_bf16_f32 v3, v4, v5
	v_pk_mul_f32 v[4:5], v[14:15], v[0:1] op_sel_hi:[1,0]
	v_pk_mul_f32 v[6:7], v[16:17], v[0:1] op_sel_hi:[1,0]
	v_pk_mul_f32 v[52:53], v[54:55], v[0:1] op_sel_hi:[1,0]
	v_pk_mul_f32 v[54:55], v[56:57], v[0:1] op_sel_hi:[1,0]
	v_cvt_pk_bf16_f32 v18, v18, v19
	v_cvt_pk_bf16_f32 v19, v20, v21
	v_pk_mul_f32 v[20:21], v[38:39], v[0:1] op_sel_hi:[1,0]
	v_pk_mul_f32 v[22:23], v[40:41], v[0:1] op_sel_hi:[1,0]
	v_cvt_pk_bf16_f32 v4, v4, v5
	v_cvt_pk_bf16_f32 v5, v6, v7
	v_cvt_pk_bf16_f32 v52, v52, v53
	v_cvt_pk_bf16_f32 v53, v54, v55
	v_cvt_pk_bf16_f32 v20, v20, v21
	v_cvt_pk_bf16_f32 v21, v22, v23
	ds_write2_b64 v67, v[2:3], v[4:5] offset0:28 offset1:30
	v_ashrrev_i32_e32 v3, 4, v66
	ds_write2_b64 v67, v[50:51], v[52:53] offset1:2
	v_pk_mul_f32 v[50:51], v[58:59], v[0:1] op_sel_hi:[1,0]
	v_pk_mul_f32 v[52:53], v[60:61], v[0:1] op_sel_hi:[1,0]
	ds_write2_b64 v67, v[18:19], v[20:21] offset0:16 offset1:18
	v_pk_mul_f32 v[18:19], v[42:43], v[0:1] op_sel_hi:[1,0]
	v_pk_mul_f32 v[20:21], v[44:45], v[0:1] op_sel_hi:[1,0]
	v_add_u32_e32 v8, s2, v3
	v_cvt_pk_bf16_f32 v50, v50, v51
	v_cvt_pk_bf16_f32 v51, v52, v53
	v_pk_mul_f32 v[52:53], v[62:63], v[0:1] op_sel_hi:[1,0]
	v_pk_mul_f32 v[54:55], v[64:65], v[0:1] op_sel_hi:[1,0]
	v_cvt_pk_bf16_f32 v18, v18, v19
	v_cvt_pk_bf16_f32 v19, v20, v21
	v_pk_mul_f32 v[20:21], v[46:47], v[0:1] op_sel_hi:[1,0]
	v_pk_mul_f32 v[22:23], v[48:49], v[0:1] op_sel_hi:[1,0]
	v_and_b32_e32 v0, 15, v66
	v_ashrrev_i32_e32 v9, 31, v8
	v_cvt_pk_bf16_f32 v52, v52, v53
	v_cvt_pk_bf16_f32 v53, v54, v55
	v_cvt_pk_bf16_f32 v20, v20, v21
	v_cvt_pk_bf16_f32 v21, v22, v23
	v_lshl_add_u32 v2, v0, 4, s93
	v_lshl_or_b32 v0, v0, 3, s3
	v_lshlrev_b64 v[8:9], 11, v[8:9]
	ds_write2_b64 v67, v[50:51], v[52:53] offset0:4 offset1:6
	ds_write2_b64 v67, v[18:19], v[20:21] offset0:20 offset1:22
	v_lshl_add_u64 v[8:9], v[8:9], 0, v[0:1]
	s_waitcnt lgkmcnt(0)
	v_lshlrev_b64 v[12:13], 1, v[8:9]
	v_lshl_add_u64 v[8:9], s[10:11], 0, v[12:13]
	s_mov_b64 s[4:5], 0x4000
	global_load_dwordx4 v[20:23], v[8:9], off
	v_lshl_add_u64 v[54:55], v[8:9], 0, s[4:5]
	global_load_dwordx4 v[24:27], v[54:55], off
	v_lshl_add_u64 v[56:57], v[54:55], 0, s[4:5]
	global_load_dwordx4 v[28:31], v[56:57], off
	v_lshl_add_u64 v[52:53], v[56:57], 0, s[4:5]
	global_load_dwordx4 v[32:35], v[52:53], off
	v_lshl_add_u64 v[54:55], v[52:53], 0, s[4:5]
	global_load_dwordx4 v[36:39], v[54:55], off
	v_lshl_add_u64 v[56:57], v[54:55], 0, s[4:5]
	global_load_dwordx4 v[40:43], v[56:57], off
	v_lshl_add_u64 v[52:53], v[56:57], 0, s[4:5]
	global_load_dwordx4 v[44:47], v[52:53], off
	v_lshl_add_u64 v[54:55], v[52:53], 0, s[4:5]
	global_load_dwordx4 v[48:51], v[54:55], off
	s_movk_i32 s3, 0x110
	v_mad_u64_u32 v[4:5], s[4:5], v3, s3, v[2:3]
	ds_read_b128 v[4:7], v4
	v_add_u32_e32 v3, 64, v66
	v_ashrrev_i32_e32 v3, 4, v3
	s_mov_b32 s23, s91
	s_mov_b32 s28, s97
	s_waitcnt lgkmcnt(0)
	v_lshlrev_b32_e32 v14, 16, v4
	v_and_b32_e32 v15, 0xffff0000, v4
	s_mov_b64 s[26:27], s[18:19]
	s_mov_b64 s[20:21], s[24:25]
	s_mov_b64 s[8:9], s[16:17]
	s_waitcnt vmcnt(7)
; #define LAS __attribute__((address_space(3)))
; __device__ __forceinline__ unsigned pk2(float lo, float hi) { f32x2 v = {lo, hi}; bf16x2_t b = __builtin_convertvector(v, bf16x2_t); return __builtin_bit_cast(unsigned, b); }
; template <int MODE> __device__ __forceinline__ void attn_unit(const Args& A, LAS unsigned char* lds, bf16x8 (&qf)[12], AttDma& D, int& bufi, int b, int h, int qb,
;                                                               bool hasn, int bn, int hn, int qbn, int tid, int wid, int lane) {
;     ...
; #pragma unroll
;     for (int k = 0; k < 8; ++k) { const int idx = lane_e + 64 * k, qq = idx >> 4, ch = idx & 15;
;         const u32x4 ov = *(const LAS u32x4*)(stg + qq * OST + ch * 16);
;         const size_t off = (size_t)(tq0 + wid * 32 + qq) * MLAW + h * DV + ch * 8;
;         const u32x4 zv = *(const u32x4*)(ZS + off);
;         u32x4 r;
;         r.x = pk2(bf_lo(ov.x) * bf_lo(zv.x), bf_hi(ov.x) * bf_hi(zv.x)); r.y = pk2(bf_lo(ov.y) * bf_lo(zv.y), bf_hi(ov.y) * bf_hi(zv.y));
;         r.z = pk2(bf_lo(ov.z) * bf_lo(zv.z), bf_hi(ov.z) * bf_hi(zv.z)); r.w = pk2(bf_lo(ov.w) * bf_lo(zv.w), bf_hi(ov.w) * bf_hi(zv.w));
;         *(u32x4*)(O + off) = r; }
	v_mov_b32_e32 v8, v20
	v_mov_b32_e32 v9, v21
	v_mov_b32_e32 v10, v22
	v_mov_b32_e32 v11, v23
	v_lshlrev_b32_e32 v16, 16, v8
	v_and_b32_e32 v17, 0xffff0000, v8
	v_pk_mul_f32 v[14:15], v[14:15], v[16:17]
	v_lshlrev_b32_e32 v8, 16, v9
	v_cvt_pk_bf16_f32 v4, v14, v15
	v_lshlrev_b32_e32 v14, 16, v5
	v_and_b32_e32 v15, 0xffff0000, v5
	v_and_b32_e32 v9, 0xffff0000, v9
	v_pk_mul_f32 v[8:9], v[14:15], v[8:9]
	v_lshlrev_b32_e32 v14, 16, v10
	v_cvt_pk_bf16_f32 v5, v8, v9
	v_lshlrev_b32_e32 v8, 16, v6
	v_and_b32_e32 v9, 0xffff0000, v6
	v_and_b32_e32 v15, 0xffff0000, v10
	v_pk_mul_f32 v[8:9], v[8:9], v[14:15]
	v_lshlrev_b32_e32 v10, 16, v11
	v_cvt_pk_bf16_f32 v6, v8, v9
	v_lshlrev_b32_e32 v8, 16, v7
	v_and_b32_e32 v9, 0xffff0000, v7
	v_and_b32_e32 v11, 0xffff0000, v11
	v_pk_mul_f32 v[8:9], v[8:9], v[10:11]
	s_nop 0
	v_cvt_pk_bf16_f32 v7, v8, v9
	v_lshl_add_u64 v[8:9], s[12:13], 0, v[12:13]
	global_store_dwordx4 v[8:9], v[4:7], off
	v_add_u32_e32 v8, s2, v3
	v_ashrrev_i32_e32 v9, 31, v8
	v_lshlrev_b64 v[8:9], 11, v[8:9]
	v_lshl_add_u64 v[8:9], v[8:9], 0, v[0:1]
	v_lshlrev_b64 v[12:13], 1, v[8:9]
	v_lshl_add_u64 v[8:9], s[10:11], 0, v[12:13]
	v_mad_u64_u32 v[4:5], s[4:5], v3, s3, v[2:3]
	ds_read_b128 v[4:7], v4
	v_add_u32_e32 v3, 0x80, v66
	v_ashrrev_i32_e32 v3, 4, v3
	s_waitcnt lgkmcnt(0)
	v_lshlrev_b32_e32 v14, 16, v4
	v_and_b32_e32 v15, 0xffff0000, v4
	s_waitcnt vmcnt(7)
	v_mov_b32_e32 v8, v24
	v_mov_b32_e32 v9, v25
	v_mov_b32_e32 v10, v26
	v_mov_b32_e32 v11, v27
	v_lshlrev_b32_e32 v16, 16, v8
	v_and_b32_e32 v17, 0xffff0000, v8
	v_pk_mul_f32 v[14:15], v[14:15], v[16:17]
	v_lshlrev_b32_e32 v8, 16, v9
	v_cvt_pk_bf16_f32 v4, v14, v15
	v_lshlrev_b32_e32 v14, 16, v5
	v_and_b32_e32 v15, 0xffff0000, v5
	v_and_b32_e32 v9, 0xffff0000, v9
	v_pk_mul_f32 v[8:9], v[14:15], v[8:9]
	v_lshlrev_b32_e32 v14, 16, v10
	v_cvt_pk_bf16_f32 v5, v8, v9
	v_lshlrev_b32_e32 v8, 16, v6
	v_and_b32_e32 v9, 0xffff0000, v6
	v_and_b32_e32 v15, 0xffff0000, v10
	v_pk_mul_f32 v[8:9], v[8:9], v[14:15]
	v_lshlrev_b32_e32 v10, 16, v11
	v_cvt_pk_bf16_f32 v6, v8, v9
	v_lshlrev_b32_e32 v8, 16, v7
	v_and_b32_e32 v9, 0xffff0000, v7
	v_and_b32_e32 v11, 0xffff0000, v11
	v_pk_mul_f32 v[8:9], v[8:9], v[10:11]
	s_nop 0
	v_cvt_pk_bf16_f32 v7, v8, v9
	v_lshl_add_u64 v[8:9], s[12:13], 0, v[12:13]
	global_store_dwordx4 v[8:9], v[4:7], off
	v_add_u32_e32 v8, s2, v3
	v_ashrrev_i32_e32 v9, 31, v8
	v_lshlrev_b64 v[8:9], 11, v[8:9]
	v_lshl_add_u64 v[8:9], v[8:9], 0, v[0:1]
	v_lshlrev_b64 v[12:13], 1, v[8:9]
	v_lshl_add_u64 v[8:9], s[10:11], 0, v[12:13]
	v_mad_u64_u32 v[4:5], s[4:5], v3, s3, v[2:3]
	ds_read_b128 v[4:7], v4
	v_add_u32_e32 v3, 0xc0, v66
	v_ashrrev_i32_e32 v3, 4, v3
	s_waitcnt lgkmcnt(0)
	v_lshlrev_b32_e32 v14, 16, v4
	v_and_b32_e32 v15, 0xffff0000, v4
	s_waitcnt vmcnt(7)
	v_mov_b32_e32 v8, v28
	v_mov_b32_e32 v9, v29
	v_mov_b32_e32 v10, v30
	v_mov_b32_e32 v11, v31
	v_lshlrev_b32_e32 v16, 16, v8
	v_and_b32_e32 v17, 0xffff0000, v8
	v_pk_mul_f32 v[14:15], v[14:15], v[16:17]
	v_lshlrev_b32_e32 v8, 16, v9
	v_cvt_pk_bf16_f32 v4, v14, v15
	v_lshlrev_b32_e32 v14, 16, v5
	v_and_b32_e32 v15, 0xffff0000, v5
	v_and_b32_e32 v9, 0xffff0000, v9
	v_pk_mul_f32 v[8:9], v[14:15], v[8:9]
	v_lshlrev_b32_e32 v14, 16, v10
	v_cvt_pk_bf16_f32 v5, v8, v9
	v_lshlrev_b32_e32 v8, 16, v6
	v_and_b32_e32 v9, 0xffff0000, v6
	v_and_b32_e32 v15, 0xffff0000, v10
	v_pk_mul_f32 v[8:9], v[8:9], v[14:15]
	v_lshlrev_b32_e32 v10, 16, v11
	v_cvt_pk_bf16_f32 v6, v8, v9
	v_lshlrev_b32_e32 v8, 16, v7
	v_and_b32_e32 v9, 0xffff0000, v7
	v_and_b32_e32 v11, 0xffff0000, v11
	v_pk_mul_f32 v[8:9], v[8:9], v[10:11]
	s_nop 0
	v_cvt_pk_bf16_f32 v7, v8, v9
	v_lshl_add_u64 v[8:9], s[12:13], 0, v[12:13]
	global_store_dwordx4 v[8:9], v[4:7], off
	v_add_u32_e32 v8, s2, v3
	v_ashrrev_i32_e32 v9, 31, v8
	v_lshlrev_b64 v[8:9], 11, v[8:9]
	v_lshl_add_u64 v[8:9], v[8:9], 0, v[0:1]
	v_lshlrev_b64 v[12:13], 1, v[8:9]
	v_lshl_add_u64 v[8:9], s[10:11], 0, v[12:13]
	v_mad_u64_u32 v[4:5], s[4:5], v3, s3, v[2:3]
	ds_read_b128 v[4:7], v4
	v_add_u32_e32 v3, 0x100, v66
	v_ashrrev_i32_e32 v3, 4, v3
	s_waitcnt lgkmcnt(0)
	v_lshlrev_b32_e32 v14, 16, v4
	v_and_b32_e32 v15, 0xffff0000, v4
	s_waitcnt vmcnt(7)
	v_mov_b32_e32 v8, v32
	v_mov_b32_e32 v9, v33
	v_mov_b32_e32 v10, v34
	v_mov_b32_e32 v11, v35
	v_lshlrev_b32_e32 v16, 16, v8
	v_and_b32_e32 v17, 0xffff0000, v8
	v_pk_mul_f32 v[14:15], v[14:15], v[16:17]
	v_lshlrev_b32_e32 v8, 16, v9
	v_cvt_pk_bf16_f32 v4, v14, v15
	v_lshlrev_b32_e32 v14, 16, v5
	v_and_b32_e32 v15, 0xffff0000, v5
	v_and_b32_e32 v9, 0xffff0000, v9
	v_pk_mul_f32 v[8:9], v[14:15], v[8:9]
	v_lshlrev_b32_e32 v14, 16, v10
	v_cvt_pk_bf16_f32 v5, v8, v9
	v_lshlrev_b32_e32 v8, 16, v6
	v_and_b32_e32 v9, 0xffff0000, v6
	v_and_b32_e32 v15, 0xffff0000, v10
	v_pk_mul_f32 v[8:9], v[8:9], v[14:15]
	v_lshlrev_b32_e32 v10, 16, v11
	v_cvt_pk_bf16_f32 v6, v8, v9
	v_lshlrev_b32_e32 v8, 16, v7
	v_and_b32_e32 v9, 0xffff0000, v7
	v_and_b32_e32 v11, 0xffff0000, v11
	v_pk_mul_f32 v[8:9], v[8:9], v[10:11]
	s_nop 0
	v_cvt_pk_bf16_f32 v7, v8, v9
	v_lshl_add_u64 v[8:9], s[12:13], 0, v[12:13]
	global_store_dwordx4 v[8:9], v[4:7], off
	v_add_u32_e32 v8, s2, v3
	v_ashrrev_i32_e32 v9, 31, v8
	v_lshlrev_b64 v[8:9], 11, v[8:9]
	v_lshl_add_u64 v[8:9], v[8:9], 0, v[0:1]
	v_lshlrev_b64 v[12:13], 1, v[8:9]
	v_lshl_add_u64 v[8:9], s[10:11], 0, v[12:13]
	v_mad_u64_u32 v[4:5], s[4:5], v3, s3, v[2:3]
	ds_read_b128 v[4:7], v4
	v_add_u32_e32 v3, 0x140, v66
	v_ashrrev_i32_e32 v3, 4, v3
	s_waitcnt lgkmcnt(0)
; #define LAS __attribute__((address_space(3)))
; __device__ __forceinline__ unsigned pk2(float lo, float hi) { f32x2 v = {lo, hi}; bf16x2_t b = __builtin_convertvector(v, bf16x2_t); return __builtin_bit_cast(unsigned, b); }
; template <int MODE> __device__ __forceinline__ void attn_unit(const Args& A, LAS unsigned char* lds, bf16x8 (&qf)[12], AttDma& D, int& bufi, int b, int h, int qb,
;                                                               bool hasn, int bn, int hn, int qbn, int tid, int wid, int lane) {
;     ...
; #pragma unroll
;     for (int k = 0; k < 8; ++k) { const int idx = lane_e + 64 * k, qq = idx >> 4, ch = idx & 15;
;         const u32x4 ov = *(const LAS u32x4*)(stg + qq * OST + ch * 16);
;         const size_t off = (size_t)(tq0 + wid * 32 + qq) * MLAW + h * DV + ch * 8;
;         const u32x4 zv = *(const u32x4*)(ZS + off);
;         u32x4 r;
;         r.x = pk2(bf_lo(ov.x) * bf_lo(zv.x), bf_hi(ov.x) * bf_hi(zv.x)); r.y = pk2(bf_lo(ov.y) * bf_lo(zv.y), bf_hi(ov.y) * bf_hi(zv.y));
;         r.z = pk2(bf_lo(ov.z) * bf_lo(zv.z), bf_hi(ov.z) * bf_hi(zv.z)); r.w = pk2(bf_lo(ov.w) * bf_lo(zv.w), bf_hi(ov.w) * bf_hi(zv.w));
;         *(u32x4*)(O + off) = r; }
;     __syncthreads();
	v_lshlrev_b32_e32 v14, 16, v4
	v_and_b32_e32 v15, 0xffff0000, v4
	s_waitcnt vmcnt(7)
	v_mov_b32_e32 v8, v36
	v_mov_b32_e32 v9, v37
	v_mov_b32_e32 v10, v38
	v_mov_b32_e32 v11, v39
	v_lshlrev_b32_e32 v16, 16, v8
	v_and_b32_e32 v17, 0xffff0000, v8
	v_pk_mul_f32 v[14:15], v[14:15], v[16:17]
	v_lshlrev_b32_e32 v8, 16, v9
	v_cvt_pk_bf16_f32 v4, v14, v15
	v_lshlrev_b32_e32 v14, 16, v5
	v_and_b32_e32 v15, 0xffff0000, v5
	v_and_b32_e32 v9, 0xffff0000, v9
	v_pk_mul_f32 v[8:9], v[14:15], v[8:9]
	v_lshlrev_b32_e32 v14, 16, v10
	v_cvt_pk_bf16_f32 v5, v8, v9
	v_lshlrev_b32_e32 v8, 16, v6
	v_and_b32_e32 v9, 0xffff0000, v6
	v_and_b32_e32 v15, 0xffff0000, v10
	v_pk_mul_f32 v[8:9], v[8:9], v[14:15]
	v_lshlrev_b32_e32 v10, 16, v11
	v_cvt_pk_bf16_f32 v6, v8, v9
	v_lshlrev_b32_e32 v8, 16, v7
	v_and_b32_e32 v9, 0xffff0000, v7
	v_and_b32_e32 v11, 0xffff0000, v11
	v_pk_mul_f32 v[8:9], v[8:9], v[10:11]
	s_nop 0
	v_cvt_pk_bf16_f32 v7, v8, v9
	v_lshl_add_u64 v[8:9], s[12:13], 0, v[12:13]
	global_store_dwordx4 v[8:9], v[4:7], off
	v_add_u32_e32 v8, s2, v3
	v_ashrrev_i32_e32 v9, 31, v8
	v_lshlrev_b64 v[8:9], 11, v[8:9]
	v_lshl_add_u64 v[8:9], v[8:9], 0, v[0:1]
	v_lshlrev_b64 v[12:13], 1, v[8:9]
	v_lshl_add_u64 v[8:9], s[10:11], 0, v[12:13]
	v_mad_u64_u32 v[4:5], s[4:5], v3, s3, v[2:3]
	ds_read_b128 v[4:7], v4
	v_add_u32_e32 v3, 0x180, v66
	v_ashrrev_i32_e32 v3, 4, v3
	s_waitcnt lgkmcnt(0)
	v_lshlrev_b32_e32 v14, 16, v4
	v_and_b32_e32 v15, 0xffff0000, v4
	s_waitcnt vmcnt(7)
	v_mov_b32_e32 v8, v40
	v_mov_b32_e32 v9, v41
	v_mov_b32_e32 v10, v42
	v_mov_b32_e32 v11, v43
	v_lshlrev_b32_e32 v16, 16, v8
	v_and_b32_e32 v17, 0xffff0000, v8
	v_pk_mul_f32 v[14:15], v[14:15], v[16:17]
	v_lshlrev_b32_e32 v8, 16, v9
	v_cvt_pk_bf16_f32 v4, v14, v15
	v_lshlrev_b32_e32 v14, 16, v5
	v_and_b32_e32 v15, 0xffff0000, v5
	v_and_b32_e32 v9, 0xffff0000, v9
	v_pk_mul_f32 v[8:9], v[14:15], v[8:9]
	v_lshlrev_b32_e32 v14, 16, v10
	v_cvt_pk_bf16_f32 v5, v8, v9
	v_lshlrev_b32_e32 v8, 16, v6
	v_and_b32_e32 v9, 0xffff0000, v6
	v_and_b32_e32 v15, 0xffff0000, v10
	v_pk_mul_f32 v[8:9], v[8:9], v[14:15]
	v_lshlrev_b32_e32 v10, 16, v11
	v_cvt_pk_bf16_f32 v6, v8, v9
	v_lshlrev_b32_e32 v8, 16, v7
	v_and_b32_e32 v9, 0xffff0000, v7
	v_and_b32_e32 v11, 0xffff0000, v11
	v_pk_mul_f32 v[8:9], v[8:9], v[10:11]
	s_nop 0
	v_cvt_pk_bf16_f32 v7, v8, v9
	v_lshl_add_u64 v[8:9], s[12:13], 0, v[12:13]
	global_store_dwordx4 v[8:9], v[4:7], off
	v_add_u32_e32 v8, s2, v3
	v_ashrrev_i32_e32 v9, 31, v8
	v_lshlrev_b64 v[8:9], 11, v[8:9]
	v_lshl_add_u64 v[8:9], v[8:9], 0, v[0:1]
	v_lshlrev_b64 v[12:13], 1, v[8:9]
	v_lshl_add_u64 v[8:9], s[10:11], 0, v[12:13]
	v_mad_u64_u32 v[4:5], s[4:5], v3, s3, v[2:3]
	ds_read_b128 v[4:7], v4
	v_add_u32_e32 v3, 0x1c0, v66
	s_waitcnt lgkmcnt(0)
	v_lshlrev_b32_e32 v14, 16, v4
	v_and_b32_e32 v15, 0xffff0000, v4
	s_waitcnt vmcnt(7)
	v_mov_b32_e32 v8, v44
	v_mov_b32_e32 v9, v45
	v_mov_b32_e32 v10, v46
	v_mov_b32_e32 v11, v47
	v_lshlrev_b32_e32 v16, 16, v8
	v_and_b32_e32 v17, 0xffff0000, v8
	v_pk_mul_f32 v[14:15], v[14:15], v[16:17]
	v_lshlrev_b32_e32 v8, 16, v9
	v_cvt_pk_bf16_f32 v4, v14, v15
	v_lshlrev_b32_e32 v14, 16, v5
	v_and_b32_e32 v15, 0xffff0000, v5
	v_and_b32_e32 v9, 0xffff0000, v9
	v_pk_mul_f32 v[8:9], v[14:15], v[8:9]
	v_lshlrev_b32_e32 v14, 16, v10
	v_cvt_pk_bf16_f32 v5, v8, v9
	v_lshlrev_b32_e32 v8, 16, v6
	v_and_b32_e32 v9, 0xffff0000, v6
	v_and_b32_e32 v15, 0xffff0000, v10
	v_pk_mul_f32 v[8:9], v[8:9], v[14:15]
	v_lshlrev_b32_e32 v10, 16, v11
	v_cvt_pk_bf16_f32 v6, v8, v9
	v_lshlrev_b32_e32 v8, 16, v7
	v_and_b32_e32 v9, 0xffff0000, v7
	v_and_b32_e32 v11, 0xffff0000, v11
	v_pk_mul_f32 v[8:9], v[8:9], v[10:11]
	s_nop 0
	v_cvt_pk_bf16_f32 v7, v8, v9
	v_lshl_add_u64 v[8:9], s[12:13], 0, v[12:13]
	global_store_dwordx4 v[8:9], v[4:7], off
	s_nop 1
	v_ashrrev_i32_e32 v6, 4, v3
	v_mad_u64_u32 v[2:3], s[4:5], v6, s3, v[2:3]
	v_add_u32_e32 v6, s2, v6
	v_ashrrev_i32_e32 v7, 31, v6
	v_lshlrev_b64 v[6:7], 11, v[6:7]
	v_lshl_add_u64 v[6:7], v[6:7], 0, v[0:1]
	v_lshlrev_b64 v[10:11], 1, v[6:7]
	v_lshl_add_u64 v[6:7], s[10:11], 0, v[10:11]
	ds_read_b128 v[2:5], v2
	s_waitcnt lgkmcnt(0)
	v_lshlrev_b32_e32 v12, 16, v2
	v_and_b32_e32 v13, 0xffff0000, v2
	s_waitcnt vmcnt(7)
	v_mov_b32_e32 v6, v48
	v_mov_b32_e32 v7, v49
	v_mov_b32_e32 v8, v50
	v_mov_b32_e32 v9, v51
	v_lshlrev_b32_e32 v14, 16, v6
	v_and_b32_e32 v15, 0xffff0000, v6
	v_pk_mul_f32 v[12:13], v[12:13], v[14:15]
	v_lshlrev_b32_e32 v6, 16, v7
	v_cvt_pk_bf16_f32 v2, v12, v13
	v_lshlrev_b32_e32 v12, 16, v3
	v_and_b32_e32 v13, 0xffff0000, v3
	v_and_b32_e32 v7, 0xffff0000, v7
	v_pk_mul_f32 v[6:7], v[12:13], v[6:7]
	v_lshlrev_b32_e32 v12, 16, v8
	v_cvt_pk_bf16_f32 v3, v6, v7
	v_lshlrev_b32_e32 v6, 16, v4
	v_and_b32_e32 v7, 0xffff0000, v4
	v_and_b32_e32 v13, 0xffff0000, v8
	v_pk_mul_f32 v[6:7], v[6:7], v[12:13]
	v_lshlrev_b32_e32 v8, 16, v9
	v_cvt_pk_bf16_f32 v4, v6, v7
	v_lshlrev_b32_e32 v6, 16, v5
	v_and_b32_e32 v7, 0xffff0000, v5
	v_and_b32_e32 v9, 0xffff0000, v9
	v_pk_mul_f32 v[6:7], v[6:7], v[8:9]
	s_nop 0
	v_cvt_pk_bf16_f32 v5, v6, v7
	v_lshl_add_u64 v[6:7], s[12:13], 0, v[10:11]
	global_store_dwordx4 v[6:7], v[2:5], off
	s_waitcnt lgkmcnt(0)
	s_barrier
	s_cbranch_scc1 .LBB0_94

; #define LAS __attribute__((address_space(3)))
; template <int MODE> __device__ __forceinline__ void attn_unit(const Args& A, LAS unsigned char* lds, bf16x8 (&qf)[12], AttDma& D, int& bufi, int b, int h, int qb,
;                                                               bool hasn, int bn, int hn, int qbn, int tid, int wid, int lane) {
;     constexpr int BUFB = ATT_BUFB, ROFF = ATT_ROFF, VOFFB = ATT_VOFFB, OST = 272;
;     const bf16* ZS = (const bf16*)(A.ws + WS_ZS); bf16* O = (bf16*)(A.ws + WS_O);
;     const int r32 = lane & 31, half = lane >> 5;
;     const int tq0 = b * SEQ + qb * 256;
;     const int ntiles = 4 * qb + 4, my_last = 4 * qb + (wid >> 1);
;     unsigned okr;
;     { const int key = tid >> 3, cc = (tid & 7) ^ ((key >> 1) & 7); okr = (unsigned)(key * DR + cc * 8); }
;     { const int nb1 = (bufi == 2) ? 0 : bufi + 1; ATT_DMA(D, nb1); }
;     asm volatile("" :: "v"(qf[0]), "v"(qf[1]), "v"(qf[2]), "v"(qf[3]), "v"(qf[4]), "v"(qf[5]), "v"(qf[6]), "v"(qf[7]), "v"(qf[8]), "v"(qf[9]), "v"(qf[10]), "v"(qf[11]));
;     f32x16 o[4];
; #pragma unroll
;     for (int d = 0; d < 4; ++d)
; #pragma unroll
;         for (int i = 0; i < 16; ++i) o[d][i] = 0.f;
;     float mrun = 0.f, lrun = 0.f;
;     const int xn0 = ((r32 & 15) ^ half) * 16, xr0 = (((r32 >> 1) & 7) ^ half) * 16;
;     for (int j = 0; j < ntiles; ++j) {
;         if (MODE & 1) asm volatile("s_waitcnt vmcnt(0)" ::: "memory"); else if (j + 1 < ntiles) asm volatile("s_waitcnt vmcnt(5)" ::: "memory"); else asm volatile("s_waitcnt vmcnt(0)" ::: "memory");
;         if (!(MODE & 16)) __builtin_amdgcn_s_barrier();
;         asm volatile("" ::: "memory");
;         if (!(MODE & 1)) if (j + 2 < ntiles) { const int nb = (bufi >= 1) ? bufi - 1 : 2; ATT_DMA(D, nb); }
.LBB0_64:
	s_mul_i32 s2, s94, 0xa000
	s_add_i32 s3, s2, 0xa000
	s_cmp_eq_u32 s94, 2
	s_cselect_b64 s[28:29], -1, 0
	s_and_b64 s[16:17], s[28:29], exec
	s_cselect_b32 s3, 0, s3
	v_mov_b32_e32 v0, v195
	v_mov_b32_e32 v2, v197
	s_add_i32 s3, s88, s3
	s_mov_b32 m0, s3
	v_lshlrev_b64 v[4:5], 1, v[0:1]
	v_lshl_add_u64 v[6:7], s[26:27], 0, v[4:5]
	s_mov_b64 s[60:61], 0x2000
	global_load_lds_dwordx4 v[6:7], off
	v_lshl_add_u64 v[6:7], v[6:7], 0, s[60:61]
	s_add_i32 m0, s3, 0x2000
	v_mov_b32_e32 v3, v1
	global_load_lds_dwordx4 v[6:7], off
	v_lshl_add_u64 v[2:3], v[2:3], 1, s[20:21]
	s_add_i32 m0, s3, 0x4000
	s_nop 0
	global_load_lds_dwordx4 v[2:3], off
	v_lshl_add_u64 v[2:3], s[8:9], 0, v[4:5]
	s_add_i32 m0, s3, 0x6000
	s_nop 0
	global_load_lds_dwordx4 v[2:3], off
	v_lshl_add_u64 v[2:3], v[2:3], 0, s[60:61]
	s_add_i32 m0, s3, 0x8000
	s_add_u32 s18, s26, 0x4000
	global_load_lds_dwordx4 v[2:3], off
	s_addc_u32 s19, s27, 0
	s_add_u32 s24, s20, 0x2000
	s_addc_u32 s25, s21, 0
	s_add_u32 s16, s8, 0x4000
	s_addc_u32 s17, s9, 0
	s_cmp_lt_i32 s23, 0
	s_waitcnt vmcnt(0) lgkmcnt(0)
	s_cbranch_scc1 .LBB0_68
	s_lshl_b32 s92, s23, 2
	s_add_i32 s30, s92, s96
	s_add_i32 s3, s2, 0xffff6000
	s_cmp_gt_i32 s94, 0
	s_cselect_b32 s3, s3, 0x14000
	v_mov_b32_e32 v2, v197
	v_mov_b32_e32 v0, v195
	s_waitcnt vmcnt(5)
	s_barrier
	s_add_i32 s3, s88, s3
	s_mov_b32 m0, s3
	v_lshlrev_b64 v[4:5], 1, v[0:1]
	v_lshl_add_u64 v[6:7], s[18:19], 0, v[4:5]
	global_load_lds_dwordx4 v[6:7], off
	v_lshl_add_u64 v[6:7], v[6:7], 0, s[60:61]
	s_add_i32 m0, s3, 0x2000
	v_mov_b32_e32 v3, v1
	global_load_lds_dwordx4 v[6:7], off
	v_lshl_add_u64 v[2:3], v[2:3], 1, s[24:25]
	s_add_i32 m0, s3, 0x4000
	s_nop 0
	global_load_lds_dwordx4 v[2:3], off
	v_lshl_add_u64 v[2:3], s[16:17], 0, v[4:5]
	s_add_i32 m0, s3, 0x6000
	s_nop 0
	global_load_lds_dwordx4 v[2:3], off
	v_lshl_add_u64 v[2:3], v[2:3], 0, s[60:61]
	s_add_i32 m0, s3, 0x8000
	s_cmp_lt_i32 s30, 0
	global_load_lds_dwordx4 v[2:3], off
	s_cbranch_scc1 .LBB0_71
; #define LAS __attribute__((address_space(3)))
; #define ATT_MMK(S, src, qd) do { if (MODE & 4) { S[qd] += __builtin_bit_cast(float, (int)src[0][0] | ((int)src[3][1] << 16)); } else { __builtin_amdgcn_s_setprio(1); _Pragma("unroll") for (int i_ = 0; i_ < 4; ++i_) S = __builtin_amdgcn_mfma_f32_32x32x16_bf16(src[i_], qf[4 * (qd) + i_], S, 0, 0, 0); __builtin_amdgcn_s_setprio(0); } } while (0)
; #define ATT_SB __builtin_amdgcn_sched_barrier(0)
; #define ATT_MAX16(S, out) do { float m_ = max3f(S[0], S[1], S[2]); _Pragma("unroll") for (int i_ = 3; i_ < 15; i_ += 2) m_ = max3f(m_, S[i_], S[i_ + 1]); out = fmaxf(m_, S[15]); } while (0)
; template <int MODE> __device__ __forceinline__ void attn_unit(const Args& A, LAS unsigned char* lds, bf16x8 (&qf)[12], AttDma& D, int& bufi, int b, int h, int qb,
;                                                               bool hasn, int bn, int hn, int qbn, int tid, int wid, int lane) {
;     ...
;         if (j <= my_last) {
;             int xn = xn0, xr = xr0; asm volatile("" : "+v"(xn), "+v"(xr));
;             const LAS unsigned char* bb = lds + bufi * BUFB;
;             constexpr float THR = 8.0f;
;             f32x16 s0, s1;
;             { const float nm = -mrun;
; #pragma unroll
;               for (int i = 0; i < 16; ++i) { s0[i] = nm; s1[i] = nm; } }
;             const LAS unsigned char* kn0 = bb + r32 * 256, * kr0 = bb + ROFF + r32 * 128;
;             const LAS unsigned char* vb = bb + VOFFB + r32 * 128;
;             bf16x8 f0[4], f1[4], f2[4], pb0[2], pb1[2];
;     ...
;             ATT_LDK(f0, 0, 0); ATT_LDK(f1, 0, 1); ATT_LDK(f2, 0, 2); ATT_SB;
;             ATT_MMK(s0, f0, 0); ATT_SB; ATT_LDK(f0, 1, 0); ATT_SB;
;             ATT_MMK(s0, f1, 1); ATT_SB; ATT_LDK(f1, 1, 1); ATT_SB;
;             ATT_MMK(s0, f2, 2); ATT_SB; ATT_LDK(f2, 1, 2); ATT_SB;
;             ATT_MMK(s1, f0, 0); ATT_SB;
;             float mx0; ATT_MAX16(s0, mx0); mx0 = fmaxf(mx0, shx<32>(mx0));
;             ATT_LDV2(f0, 0, 1, 0); ATT_SB;
;             float dm0; ATT_RESCALE(mx0, s0, j == 0, dm0);
	v_mov_b32_e32 v0, v201
	v_mov_b32_e32 v2, v202
	s_add_i32 s2, s2, 0
	v_add_u32_e32 v3, s2, v203
	s_movk_i32 s3, 0x60
	v_add_u32_e32 v4, s2, v211
	s_movk_i32 s2, 0xe0
	v_add_u32_e32 v50, v3, v0
	v_xad_u32 v51, v0, 32, v3
	v_xad_u32 v52, v0, 64, v3
	v_xad_u32 v53, v0, s3, v3
	v_xad_u32 v54, v0, s75, v3
	v_xad_u32 v55, v0, s73, v3
	v_xad_u32 v56, v0, s81, v3
	v_xad_u32 v0, v0, s2, v3
	v_xor_b32_e32 v3, 32, v2
	v_add_u32_e32 v83, v4, v3
	v_xor_b32_e32 v3, 64, v2
	v_add_u32_e32 v82, v4, v2
	v_add_u32_e32 v90, v4, v3
	v_xor_b32_e32 v2, 0x60, v2
	ds_read_b128 v[18:21], v50
	ds_read_b128 v[22:25], v51
	ds_read_b128 v[26:29], v52
	ds_read_b128 v[30:33], v53
	ds_read_b128 v[34:37], v54
	ds_read_b128 v[38:41], v55
	ds_read_b128 v[42:45], v56
	ds_read_b128 v[46:49], v0
	ds_read_b128 v[84:87], v82 offset:16384
	ds_read_b128 v[92:95], v83 offset:16384
	v_add_u32_e32 v91, v4, v2
	ds_read_b128 v[146:149], v90 offset:16384
	ds_read_b128 v[150:153], v91 offset:16384
	s_mov_b32 s34, s58
	s_mov_b32 s31, s59
	s_mov_b32 s19, s57
	s_mov_b64 s[24:25], s[62:63]
	s_mov_b32 s17, s53
	s_mov_b32 s18, s52
	s_setprio 1
	v_readlane_b32 s52, v249, 35
	v_readlane_b32 s66, v249, 49
	v_readlane_b32 s67, v249, 50
	v_readlane_b32 s53, v249, 36
	v_readlane_b32 s54, v249, 37
	v_readlane_b32 s55, v249, 38
	v_readlane_b32 s56, v249, 39
	v_readlane_b32 s57, v249, 40
	v_readlane_b32 s58, v249, 41
	v_readlane_b32 s59, v249, 42
	v_readlane_b32 s60, v249, 43
	v_readlane_b32 s61, v249, 44
	v_readlane_b32 s62, v249, 45
	v_readlane_b32 s63, v249, 46
	v_readlane_b32 s64, v249, 47
	v_readlane_b32 s65, v249, 48
	s_mov_b32 s66, s52
	s_mov_b32 s67, s52
	s_mov_b32 s53, s52
	s_mov_b32 s54, s52
	s_mov_b32 s55, s52
	s_mov_b32 s56, s52
	s_mov_b32 s57, s52
	s_mov_b32 s58, s52
	s_mov_b32 s59, s52
	s_mov_b32 s60, s52
	s_mov_b32 s61, s52
	s_mov_b32 s62, s52
	s_mov_b32 s63, s52
	s_mov_b32 s64, s52
	s_mov_b32 s65, s52
	v_mov_b64_e32 v[80:81], s[66:67]
	v_mov_b64_e32 v[78:79], s[64:65]
	v_mov_b64_e32 v[76:77], s[62:63]
	v_mov_b64_e32 v[74:75], s[60:61]
	v_mov_b64_e32 v[72:73], s[58:59]
	v_mov_b64_e32 v[70:71], s[56:57]
	v_mov_b64_e32 v[68:69], s[54:55]
	v_mov_b64_e32 v[66:67], s[52:53]
	s_mov_b32 s16, s52
	v_writelane_b32 v249, s16, 35
	s_waitcnt lgkmcnt(0)
	v_mfma_f32_32x32x16_bf16 v[2:17], v[18:21], v[98:101], v[66:81]
	v_writelane_b32 v249, s17, 36
	v_writelane_b32 v249, s18, 37
	v_writelane_b32 v249, s19, 38
	v_writelane_b32 v249, s20, 39
	v_writelane_b32 v249, s21, 40
	v_writelane_b32 v249, s22, 41
	v_mfma_f32_32x32x16_bf16 v[2:17], v[22:25], v[102:105], v[2:17]
	v_writelane_b32 v249, s23, 42
	v_writelane_b32 v249, s24, 43
	v_writelane_b32 v249, s25, 44
	v_writelane_b32 v249, s26, 45
	v_writelane_b32 v249, s27, 46
	v_writelane_b32 v249, s28, 47
	v_writelane_b32 v249, s29, 48
	v_mfma_f32_32x32x16_bf16 v[2:17], v[26:29], v[106:109], v[2:17]
	v_writelane_b32 v249, s30, 49
	v_writelane_b32 v249, s31, 50
	v_mfma_f32_32x32x16_bf16 v[2:17], v[30:33], v[110:113], v[2:17]
	s_setprio 0
	ds_read_b128 v[18:21], v50 offset:8192
	ds_read_b128 v[22:25], v51 offset:8192
	ds_read_b128 v[154:157], v52 offset:8192
	ds_read_b128 v[158:161], v53 offset:8192
	s_setprio 1
	v_mfma_f32_32x32x16_bf16 v[2:17], v[34:37], v[114:117], v[2:17]
	v_mfma_f32_32x32x16_bf16 v[2:17], v[38:41], v[118:121], v[2:17]
	v_mfma_f32_32x32x16_bf16 v[2:17], v[42:45], v[122:125], v[2:17]
	v_mfma_f32_32x32x16_bf16 v[2:17], v[46:49], v[126:129], v[2:17]
	s_setprio 0
	ds_read_b128 v[62:65], v54 offset:8192
	ds_read_b128 v[58:61], v55 offset:8192
	ds_read_b128 v[54:57], v56 offset:8192
	ds_read_b128 v[50:53], v0 offset:8192
	s_setprio 1
	v_mfma_f32_32x32x16_bf16 v[2:17], v[84:87], v[130:133], v[2:17]
	v_mfma_f32_32x32x16_bf16 v[2:17], v[92:95], v[134:137], v[2:17]
	v_mfma_f32_32x32x16_bf16 v[2:17], v[146:149], v[138:141], v[2:17]
	v_mfma_f32_32x32x16_bf16 v[2:17], v[150:153], v[142:145], v[2:17]
	s_setprio 0
	ds_read_b128 v[46:49], v82 offset:20480
	ds_read_b128 v[42:45], v83 offset:20480
	ds_read_b128 v[30:33], v90 offset:20480
	ds_read_b128 v[26:29], v91 offset:20480
	s_setprio 1
	s_waitcnt lgkmcnt(0)
	v_mfma_f32_32x32x16_bf16 v[66:81], v[18:21], v[98:101], v[66:81]
	v_mfma_f32_32x32x16_bf16 v[66:81], v[22:25], v[102:105], v[66:81]
	v_mfma_f32_32x32x16_bf16 v[66:81], v[154:157], v[106:109], v[66:81]
	v_mfma_f32_32x32x16_bf16 v[66:81], v[158:161], v[110:113], v[66:81]
	s_setprio 0
	v_max3_f32 v0, v2, v3, v4
	v_max_f32_e32 v18, v17, v17
	v_max3_f32 v0, v0, v5, v6
	s_nop 0
	v_max3_f32 v0, v0, v7, v8
	s_nop 0
	v_max3_f32 v0, v0, v9, v10
	s_nop 0
	v_max3_f32 v0, v0, v11, v12
	s_nop 0
	v_max3_f32 v0, v0, v13, v14
	s_nop 0
	v_max3_f32 v0, v0, v15, v16
	s_nop 0
	v_max_f32_e32 v0, v0, v0
	v_max_f32_e32 v0, v0, v18
	v_mbcnt_lo_u32_b32 v18, -1, 0
	v_mbcnt_hi_u32_b32 v18, -1, v18
	s_nop 0
	v_lshlrev_b32_e32 v18, 2, v18
	v_xor_b32_e32 v18, 0x80, v18
	ds_bpermute_b32 v18, v18, v0
	s_waitcnt lgkmcnt(0)
	v_max_f32_e32 v18, v18, v18
	v_max_f32_e32 v0, v0, v18
	ds_read_b128 v[18:21], v82 offset:24576
	ds_read_b128 v[34:37], v83 offset:24576
	ds_read_b128 v[22:25], v82 offset:28672
	ds_read_b128 v[38:41], v83 offset:28672
	s_cmp_eq_u64 exec, 0
	s_cbranch_scc1 .LBB0_72
	v_add_f32_e32 v212, 0, v0
	v_pk_add_f32 v[2:3], v[2:3], v[0:1] op_sel_hi:[1,0] neg_lo:[0,1] neg_hi:[0,1]
	v_pk_add_f32 v[4:5], v[4:5], v[0:1] op_sel_hi:[1,0] neg_lo:[0,1] neg_hi:[0,1]
	v_pk_add_f32 v[6:7], v[6:7], v[0:1] op_sel_hi:[1,0] neg_lo:[0,1] neg_hi:[0,1]
	v_pk_add_f32 v[8:9], v[8:9], v[0:1] op_sel_hi:[1,0] neg_lo:[0,1] neg_hi:[0,1]
	v_pk_add_f32 v[10:11], v[10:11], v[0:1] op_sel_hi:[1,0] neg_lo:[0,1] neg_hi:[0,1]
	v_pk_add_f32 v[12:13], v[12:13], v[0:1] op_sel_hi:[1,0] neg_lo:[0,1] neg_hi:[0,1]
	v_pk_add_f32 v[14:15], v[14:15], v[0:1] op_sel_hi:[1,0] neg_lo:[0,1] neg_hi:[0,1]
	v_pk_add_f32 v[16:17], v[16:17], v[0:1] op_sel_hi:[1,0] neg_lo:[0,1] neg_hi:[0,1]
	s_branch .LBB0_73
	s_nop 0
	s_nop 0
	s_nop 0
	s_nop 0
	s_nop 0
	s_nop 0
	s_nop 0
	s_nop 0
	s_nop 0
	s_nop 0
	s_nop 0
	s_nop 0
	s_nop 0
	s_nop 0
	s_nop 0
	s_nop 0

; __device__ __forceinline__ unsigned pk2(float lo, float hi) { f32x2 v = {lo, hi}; bf16x2_t b = __builtin_convertvector(v, bf16x2_t); return __builtin_bit_cast(unsigned, b); }
;     __device__ __forceinline__ void operator()(AccT& acc, const Unit& u, int wr, int wc, int fr, int fq) const {
;     ...
;         const int row0 = u.pm * BM + wr * 64 + fr, col0 = u.pn * BM + wc * 32 + 8 * fq;
; #pragma unroll
;         for (int ai = 0; ai < 2; ++ai)
; #pragma unroll
;             for (int m = 0; m < 4; ++m) { const int row = row0 + ai * HALF + m * 16; bf16_t* rowp = Q + (size_t)row * (NH * DQK) + col0;
;                 const float r = rsq[row] * QSCALE; const int pos = row & (SEQ - 1);
; #pragma unroll
;                 for (int bj = 0; bj < 2; ++bj) { f32x4 v0 = acc[ai][bj][m][0], v1 = acc[ai][bj][m][1];
;                     const int cl = (col0 + bj * HALF) % DQK;
;                     if (cl >= DN) { const f32x4* cp = (const f32x4*)(cs + (size_t)pos * 32 + ((cl - DN) >> 1)); const f32x4 c0 = cp[0], c1 = cp[1];
;                         f32x4 t0, t1;
;                         t0[0] = v0[0] * c0[0] - v0[1] * c0[1]; t0[1] = v0[0] * c0[1] + v0[1] * c0[0];
;                         t0[2] = v0[2] * c0[2] - v0[3] * c0[3]; t0[3] = v0[2] * c0[3] + v0[3] * c0[2];
;                         t1[0] = v1[0] * c1[0] - v1[1] * c1[1]; t1[1] = v1[0] * c1[1] + v1[1] * c1[0];
;                         t1[2] = v1[2] * c1[2] - v1[3] * c1[3]; t1[3] = v1[2] * c1[3] + v1[3] * c1[2];
;                         v0 = t0; v1 = t1; }
;                     v0 = v0 * r; v1 = v1 * r;
;                     u32x4 w; w.x = pk2(v0[0], v0[1]); w.y = pk2(v0[2], v0[3]); w.z = pk2(v1[0], v1[1]); w.w = pk2(v1[2], v1[3]);
;                     *(u32x4*)(rowp + bj * HALF) = w; } }
.LBB0_112:
	v_lshl_add_u32 v146, s8, 8, v154
	v_ashrrev_i32_e32 v147, 31, v146
	v_lshl_add_u64 v[148:149], v[146:147], 2, s[18:19]
	flat_load_dword v147, v[148:149]
	v_lshl_or_b32 v142, s0, 8, v156
	v_mul_hi_i32 v143, v142, s87
	v_lshrrev_b32_e32 v144, 31, v143
	v_lshrrev_b32_e32 v143, 5, v143
	v_add_u32_e32 v143, v143, v144
	v_mul_lo_u32 v143, v143, s81
	v_lshlrev_b32_e32 v0, 5, v146
	v_sub_u32_e32 v143, v142, v143
	s_movk_i32 s0, 0x7f
	v_and_b32_e32 v0, 0x1f9e0, v0
	v_cmp_lt_i32_e32 vcc, s0, v143
	v_add_u32_e32 v143, 0xffffff80, v143
	v_lshlrev_b32_e32 v0, 3, v0
	v_lshrrev_b32_e32 v144, 1, v143
	v_lshlrev_b32_e32 v253, 2, v146
	global_load_dword v169, v253, s[18:19] offset:64
	global_load_dword v170, v253, s[18:19] offset:128
	global_load_dword v171, v253, s[18:19] offset:192
	global_load_dword v172, v253, s[18:19] offset:512
	global_load_dword v173, v253, s[18:19] offset:576
	global_load_dword v174, v253, s[18:19] offset:640
	global_load_dword v175, v253, s[18:19] offset:704
	v_or_b32_e32 v251, 0x80, v142
	v_mul_hi_i32 v254, v251, s87
	v_lshrrev_b32_e32 v255, 31, v254
	v_lshrrev_b32_e32 v254, 5, v254
	v_add_u32_e32 v254, v254, v255
	v_mul_lo_u32 v254, v254, s81
	v_sub_u32_e32 v251, v251, v254
	v_mov_b32_e32 v254, 0x7f
	v_cmp_gt_i32_e64 s[100:101], v251, v254
	v_add_u32_e32 v251, 0xffffff80, v251
	v_lshrrev_b32_e32 v251, 1, v251
	v_lshl_add_u32 v255, v251, 3, v0
	v_lshl_add_u32 v252, v144, 3, v0
	v_cndmask_b32_e32 v252, v255, v252, vcc
	s_nop 3
	s_or_b64 s[100:101], s[100:101], vcc
	s_mov_b64 exec, s[100:101]
	s_cbranch_execz .Lq_top_skip
	global_load_dwordx4 v[176:179], v252, s[24:25]
	global_load_dwordx4 v[180:183], v252, s[24:25] offset:16
	v_add_u32_e32 v253, 0x1000, v252
	global_load_dwordx4 v[184:187], v253, s[24:25]
	global_load_dwordx4 v[188:191], v253, s[24:25] offset:16
	v_add_u32_e32 v254, 0x2000, v252
	global_load_dwordx4 v[198:201], v254, s[24:25]
	global_load_dwordx4 v[212:215], v254, s[24:25] offset:16
	v_add_u32_e32 v255, 0x3000, v252
	global_load_dwordx4 v[216:219], v255, s[24:25]
	global_load_dwordx4 v[220:223], v255, s[24:25] offset:16
.Lq_top_skip:
	s_mov_b64 exec, -1
	s_and_saveexec_b64 s[0:1], vcc
	s_cbranch_execz .LBB0_114
	v_lshl_add_u64 v[150:151], s[24:25], 0, v[0:1]
	v_mov_b32_e32 v145, v1
	v_lshl_add_u64 v[158:159], v[144:145], 3, v[150:151]
	s_nop 0
	s_waitcnt vmcnt(0) lgkmcnt(0)
	v_mov_b32_e32 v150, v176
	v_mov_b32_e32 v151, v177
	v_mov_b32_e32 v152, v178
	v_mov_b32_e32 v153, v179
	v_mov_b32_e32 v158, v180
	v_mov_b32_e32 v159, v181
	v_mov_b32_e32 v160, v182
	v_mov_b32_e32 v161, v183
	v_pk_mul_f32 v[164:165], v[126:127], v[150:151] op_sel:[1,1] op_sel_hi:[1,0]
	v_pk_mul_f32 v[162:163], v[126:127], v[150:151]
	v_pk_fma_f32 v[126:127], v[126:127], v[150:151], v[164:165] op_sel_hi:[0,1,1]
	v_mul_f32_e32 v126, v129, v153
	v_pk_fma_f32 v[150:151], v[128:129], v[152:153], v[126:127] op_sel_hi:[1,1,0] neg_lo:[0,0,1] neg_hi:[0,0,1]
	v_mul_f32_e32 v126, v129, v152
	v_pk_mul_f32 v[166:167], v[122:123], v[158:159] op_sel:[1,1] op_sel_hi:[1,0]
	v_pk_fma_f32 v[152:153], v[128:129], v[152:153], v[126:127] op_sel:[0,1,0] op_sel_hi:[1,0,0]
	v_pk_mul_f32 v[128:129], v[122:123], v[158:159]
	v_pk_fma_f32 v[122:123], v[122:123], v[158:159], v[166:167] op_sel_hi:[0,1,1]
	v_mul_f32_e32 v122, v125, v161
	v_pk_fma_f32 v[158:159], v[124:125], v[160:161], v[122:123] op_sel_hi:[1,1,0] neg_lo:[0,0,1] neg_hi:[0,0,1]
	v_mul_f32_e32 v122, v125, v160
	v_pk_fma_f32 v[160:161], v[124:125], v[160:161], v[122:123] op_sel:[0,1,0] op_sel_hi:[1,0,0]
	v_sub_f32_e32 v126, v162, v164
	v_sub_f32_e32 v122, v128, v166
	v_mov_b32_e32 v128, v150
	v_mov_b32_e32 v129, v152
	v_mov_b32_e32 v124, v158
	v_mov_b32_e32 v125, v160
.LBB0_114:
	s_or_b64 exec, exec, s[0:1]
	v_mov_b64_e32 v[150:151], s[16:17]
	s_movk_i32 s8, 0x1800
	s_waitcnt vmcnt(0) lgkmcnt(0)
	v_mul_f32_e32 v152, 0x3dd53b94, v147
	v_ashrrev_i32_e32 v143, 31, v142
	v_mad_i64_i32 v[150:151], s[0:1], v146, s8, v[150:151]
	v_pk_mul_f32 v[128:129], v[152:153], v[128:129] op_sel_hi:[0,1]
	v_pk_mul_f32 v[126:127], v[152:153], v[126:127] op_sel_hi:[0,1]
	v_pk_mul_f32 v[158:159], v[152:153], v[124:125] op_sel_hi:[0,1]
	v_pk_mul_f32 v[124:125], v[152:153], v[122:123] op_sel_hi:[0,1]
	v_lshl_add_u64 v[150:151], v[142:143], 1, v[150:151]
	v_cvt_pk_bf16_f32 v122, v126, v127
	v_cvt_pk_bf16_f32 v123, v128, v129
	v_cvt_pk_bf16_f32 v124, v124, v125
	v_cvt_pk_bf16_f32 v125, v158, v159
	flat_store_dwordx4 v[150:151], v[122:125]
	s_movk_i32 s0, 0x7f
	s_nop 0
	v_or_b32_e32 v122, 0x80, v142
	v_mul_hi_i32 v123, v122, s87
	v_lshrrev_b32_e32 v124, 31, v123
	v_lshrrev_b32_e32 v123, 5, v123
	v_add_u32_e32 v123, v123, v124
	v_mul_lo_u32 v123, v123, s81
	v_sub_u32_e32 v122, v122, v123
	v_cmp_lt_i32_e64 s[0:1], s0, v122
	v_add_u32_e32 v122, 0xffffff80, v122
	v_lshrrev_b32_e32 v122, 1, v122
	s_and_saveexec_b64 s[2:3], s[0:1]
	s_cbranch_execz .LBB0_116
	v_lshl_add_u64 v[124:125], s[24:25], 0, v[0:1]
	v_mov_b32_e32 v123, v1
	v_lshl_add_u64 v[128:129], v[122:123], 3, v[124:125]
	v_mov_b32_e32 v124, v176
	v_mov_b32_e32 v125, v177
	v_mov_b32_e32 v126, v178
	v_mov_b32_e32 v127, v179
	v_mov_b32_e32 v158, v180
	v_mov_b32_e32 v159, v181
	v_mov_b32_e32 v160, v182
	v_mov_b32_e32 v161, v183
	v_pk_mul_f32 v[162:163], v[118:119], v[124:125] op_sel:[1,1] op_sel_hi:[1,0]
	v_mul_f32_e32 v0, v121, v127
	v_pk_mul_f32 v[128:129], v[118:119], v[124:125]
	v_pk_fma_f32 v[118:119], v[118:119], v[124:125], v[162:163] op_sel_hi:[0,1,1]
	v_pk_fma_f32 v[124:125], v[120:121], v[126:127], v[0:1] op_sel_hi:[1,1,0] neg_lo:[0,0,1] neg_hi:[0,0,1]
	v_mul_f32_e32 v0, v121, v126
	v_pk_fma_f32 v[126:127], v[120:121], v[126:127], v[0:1] op_sel:[0,1,0] op_sel_hi:[1,0,0]
	v_pk_mul_f32 v[164:165], v[114:115], v[158:159] op_sel:[1,1] op_sel_hi:[1,0]
	v_mul_f32_e32 v0, v117, v161
	v_pk_mul_f32 v[120:121], v[114:115], v[158:159]
	v_pk_fma_f32 v[114:115], v[114:115], v[158:159], v[164:165] op_sel_hi:[0,1,1]
	v_pk_fma_f32 v[158:159], v[116:117], v[160:161], v[0:1] op_sel_hi:[1,1,0] neg_lo:[0,0,1] neg_hi:[0,0,1]
	v_mul_f32_e32 v0, v117, v160
	v_pk_fma_f32 v[160:161], v[116:117], v[160:161], v[0:1] op_sel:[0,1,0] op_sel_hi:[1,0,0]
	v_sub_f32_e32 v118, v128, v162
	v_sub_f32_e32 v114, v120, v164
	v_mov_b32_e32 v120, v124
	v_mov_b32_e32 v121, v126
	v_mov_b32_e32 v116, v158
	v_mov_b32_e32 v117, v160
; __device__ __forceinline__ unsigned pk2(float lo, float hi) { f32x2 v = {lo, hi}; bf16x2_t b = __builtin_convertvector(v, bf16x2_t); return __builtin_bit_cast(unsigned, b); }
;     __device__ __forceinline__ void operator()(AccT& acc, const Unit& u, int wr, int wc, int fr, int fq) const {
;     ...
;             for (int m = 0; m < 4; ++m) { const int row = row0 + ai * HALF + m * 16; bf16_t* rowp = Q + (size_t)row * (NH * DQK) + col0;
;                 const float r = rsq[row] * QSCALE; const int pos = row & (SEQ - 1);
; #pragma unroll
;                 for (int bj = 0; bj < 2; ++bj) { f32x4 v0 = acc[ai][bj][m][0], v1 = acc[ai][bj][m][1];
;                     const int cl = (col0 + bj * HALF) % DQK;
;                     if (cl >= DN) { const f32x4* cp = (const f32x4*)(cs + (size_t)pos * 32 + ((cl - DN) >> 1)); const f32x4 c0 = cp[0], c1 = cp[1];
;                         f32x4 t0, t1;
;                         t0[0] = v0[0] * c0[0] - v0[1] * c0[1]; t0[1] = v0[0] * c0[1] + v0[1] * c0[0];
;                         t0[2] = v0[2] * c0[2] - v0[3] * c0[3]; t0[3] = v0[2] * c0[3] + v0[3] * c0[2];
;                         t1[0] = v1[0] * c1[0] - v1[1] * c1[1]; t1[1] = v1[0] * c1[1] + v1[1] * c1[0];
;                         t1[2] = v1[2] * c1[2] - v1[3] * c1[3]; t1[3] = v1[2] * c1[3] + v1[3] * c1[2];
;                         v0 = t0; v1 = t1; }
;                     v0 = v0 * r; v1 = v1 * r;
;                     u32x4 w; w.x = pk2(v0[0], v0[1]); w.y = pk2(v0[2], v0[3]); w.z = pk2(v1[0], v1[1]); w.w = pk2(v1[2], v1[3]);
;                     *(u32x4*)(rowp + bj * HALF) = w; } }
.LBB0_116:
	s_or_b64 exec, exec, s[2:3]
	v_mov_b32_e32 v153, v152
	v_mov_b32_e32 v124, v152
	v_mov_b32_e32 v125, v152
	v_pk_mul_f32 v[120:121], v[124:125], v[120:121]
	v_pk_mul_f32 v[118:119], v[152:153], v[118:119]
	v_pk_mul_f32 v[124:125], v[124:125], v[116:117]
	v_pk_mul_f32 v[116:117], v[152:153], v[114:115]
	v_cvt_pk_bf16_f32 v114, v118, v119
	v_cvt_pk_bf16_f32 v115, v120, v121
	v_cvt_pk_bf16_f32 v116, v116, v117
	v_cvt_pk_bf16_f32 v117, v124, v125
	flat_store_dwordx4 v[150:151], v[114:117] offset:256
	s_nop 1
	v_or_b32_e32 v114, 16, v146
	v_ashrrev_i32_e32 v115, 31, v114
	v_lshl_add_u64 v[116:117], v[114:115], 2, s[18:19]
	s_nop 0
	v_lshlrev_b32_e32 v0, 5, v114
	v_and_b32_e32 v0, 0x1fbe0, v0
	v_lshlrev_b32_e32 v0, 3, v0
	s_and_saveexec_b64 s[2:3], vcc
	s_cbranch_execz .LBB0_118
	v_lshl_add_u64 v[118:119], s[24:25], 0, v[0:1]
	v_mov_b32_e32 v145, v1
	v_lshl_add_u64 v[124:125], v[144:145], 3, v[118:119]
	s_nop 0
	v_mov_b32_e32 v118, v184
	v_mov_b32_e32 v119, v185
	v_mov_b32_e32 v120, v186
	v_mov_b32_e32 v121, v187
	v_mov_b32_e32 v124, v188
	v_mov_b32_e32 v125, v189
	v_mov_b32_e32 v126, v190
	v_mov_b32_e32 v127, v191
	v_pk_mul_f32 v[150:151], v[110:111], v[118:119] op_sel:[1,1] op_sel_hi:[1,0]
	v_pk_mul_f32 v[128:129], v[110:111], v[118:119]
	v_pk_fma_f32 v[110:111], v[110:111], v[118:119], v[150:151] op_sel_hi:[0,1,1]
	v_mul_f32_e32 v110, v113, v121
	v_pk_fma_f32 v[118:119], v[112:113], v[120:121], v[110:111] op_sel_hi:[1,1,0] neg_lo:[0,0,1] neg_hi:[0,0,1]
	v_mul_f32_e32 v110, v113, v120
	v_pk_mul_f32 v[152:153], v[106:107], v[124:125] op_sel:[1,1] op_sel_hi:[1,0]
	v_pk_fma_f32 v[120:121], v[112:113], v[120:121], v[110:111] op_sel:[0,1,0] op_sel_hi:[1,0,0]
	v_pk_mul_f32 v[112:113], v[106:107], v[124:125]
	v_pk_fma_f32 v[106:107], v[106:107], v[124:125], v[152:153] op_sel_hi:[0,1,1]
	v_mul_f32_e32 v106, v109, v127
	v_pk_fma_f32 v[124:125], v[108:109], v[126:127], v[106:107] op_sel_hi:[1,1,0] neg_lo:[0,0,1] neg_hi:[0,0,1]
	v_mul_f32_e32 v106, v109, v126
	v_pk_fma_f32 v[126:127], v[108:109], v[126:127], v[106:107] op_sel:[0,1,0] op_sel_hi:[1,0,0]
	v_sub_f32_e32 v110, v128, v150
	v_sub_f32_e32 v106, v112, v152
	v_mov_b32_e32 v112, v118
	v_mov_b32_e32 v113, v120
	v_mov_b32_e32 v108, v124
	v_mov_b32_e32 v109, v126
.LBB0_118:
	s_or_b64 exec, exec, s[2:3]
	v_mov_b64_e32 v[118:119], s[16:17]
	v_mov_b32_e32 v116, v169
	v_mul_f32_e32 v116, 0x3dd53b94, v116
	v_mad_i64_i32 v[114:115], s[2:3], v114, s8, v[118:119]
	v_pk_mul_f32 v[112:113], v[116:117], v[112:113] op_sel_hi:[0,1]
	v_pk_mul_f32 v[110:111], v[116:117], v[110:111] op_sel_hi:[0,1]
	v_pk_mul_f32 v[118:119], v[116:117], v[108:109] op_sel_hi:[0,1]
	v_pk_mul_f32 v[108:109], v[116:117], v[106:107] op_sel_hi:[0,1]
	v_lshl_add_u64 v[114:115], v[142:143], 1, v[114:115]
	v_cvt_pk_bf16_f32 v106, v110, v111
	v_cvt_pk_bf16_f32 v107, v112, v113
	v_cvt_pk_bf16_f32 v108, v108, v109
	v_cvt_pk_bf16_f32 v109, v118, v119
	flat_store_dwordx4 v[114:115], v[106:109]
	s_and_saveexec_b64 s[2:3], s[0:1]
	s_cbranch_execz .LBB0_120
	v_lshl_add_u64 v[106:107], s[24:25], 0, v[0:1]
	v_mov_b32_e32 v123, v1
	v_lshl_add_u64 v[110:111], v[122:123], 3, v[106:107]
	s_nop 0
	v_mov_b32_e32 v106, v184
	v_mov_b32_e32 v107, v185
	v_mov_b32_e32 v108, v186
	v_mov_b32_e32 v109, v187
	v_mov_b32_e32 v110, v188
	v_mov_b32_e32 v111, v189
	v_mov_b32_e32 v112, v190
	v_mov_b32_e32 v113, v191
	v_pk_mul_f32 v[120:121], v[102:103], v[106:107] op_sel:[1,1] op_sel_hi:[1,0]
	v_mul_f32_e32 v0, v105, v109
	v_pk_mul_f32 v[118:119], v[102:103], v[106:107]
	v_pk_fma_f32 v[102:103], v[102:103], v[106:107], v[120:121] op_sel_hi:[0,1,1]
	v_pk_fma_f32 v[106:107], v[104:105], v[108:109], v[0:1] op_sel_hi:[1,1,0] neg_lo:[0,0,1] neg_hi:[0,0,1]
	v_mul_f32_e32 v0, v105, v108
	v_pk_fma_f32 v[108:109], v[104:105], v[108:109], v[0:1] op_sel:[0,1,0] op_sel_hi:[1,0,0]
	v_pk_mul_f32 v[124:125], v[98:99], v[110:111] op_sel:[1,1] op_sel_hi:[1,0]
	v_mul_f32_e32 v0, v101, v113
	v_pk_mul_f32 v[104:105], v[98:99], v[110:111]
	v_pk_fma_f32 v[98:99], v[98:99], v[110:111], v[124:125] op_sel_hi:[0,1,1]
	v_pk_fma_f32 v[110:111], v[100:101], v[112:113], v[0:1] op_sel_hi:[1,1,0] neg_lo:[0,0,1] neg_hi:[0,0,1]
	v_mul_f32_e32 v0, v101, v112
	v_pk_fma_f32 v[112:113], v[100:101], v[112:113], v[0:1] op_sel:[0,1,0] op_sel_hi:[1,0,0]
	v_sub_f32_e32 v102, v118, v120
	v_sub_f32_e32 v98, v104, v124
	v_mov_b32_e32 v104, v106
	v_mov_b32_e32 v105, v108
	v_mov_b32_e32 v100, v110
	v_mov_b32_e32 v101, v112
.LBB0_120:
	s_or_b64 exec, exec, s[2:3]
	v_mov_b32_e32 v117, v116
	v_mov_b32_e32 v106, v116
	v_mov_b32_e32 v107, v116
	v_pk_mul_f32 v[104:105], v[106:107], v[104:105]
	v_pk_mul_f32 v[102:103], v[116:117], v[102:103]
	v_pk_mul_f32 v[106:107], v[106:107], v[100:101]
	v_pk_mul_f32 v[100:101], v[116:117], v[98:99]
	v_cvt_pk_bf16_f32 v98, v102, v103
	v_cvt_pk_bf16_f32 v99, v104, v105
	v_cvt_pk_bf16_f32 v100, v100, v101
	v_cvt_pk_bf16_f32 v101, v106, v107
	flat_store_dwordx4 v[114:115], v[98:101] offset:256
	s_nop 1
	v_or_b32_e32 v98, 32, v146
	v_ashrrev_i32_e32 v99, 31, v98
	v_lshl_add_u64 v[100:101], v[98:99], 2, s[18:19]
	s_nop 0
	v_lshlrev_b32_e32 v0, 5, v98
	v_and_b32_e32 v0, 0x1fde0, v0
	v_lshlrev_b32_e32 v0, 3, v0
	s_and_saveexec_b64 s[2:3], vcc
	s_cbranch_execz .LBB0_122
	v_lshl_add_u64 v[102:103], s[24:25], 0, v[0:1]
	v_mov_b32_e32 v145, v1
	v_lshl_add_u64 v[106:107], v[144:145], 3, v[102:103]
	s_nop 0
	v_mov_b32_e32 v102, v198
	v_mov_b32_e32 v103, v199
	v_mov_b32_e32 v104, v200
	v_mov_b32_e32 v105, v201
	v_mov_b32_e32 v106, v212
	v_mov_b32_e32 v107, v213
	v_mov_b32_e32 v108, v214
	v_mov_b32_e32 v109, v215
	v_pk_mul_f32 v[112:113], v[94:95], v[102:103] op_sel:[1,1] op_sel_hi:[1,0]
	v_pk_mul_f32 v[110:111], v[94:95], v[102:103]
	v_pk_fma_f32 v[94:95], v[94:95], v[102:103], v[112:113] op_sel_hi:[0,1,1]
	v_mul_f32_e32 v94, v97, v105
	v_pk_fma_f32 v[102:103], v[96:97], v[104:105], v[94:95] op_sel_hi:[1,1,0] neg_lo:[0,0,1] neg_hi:[0,0,1]
	v_mul_f32_e32 v94, v97, v104
	v_pk_mul_f32 v[114:115], v[90:91], v[106:107] op_sel:[1,1] op_sel_hi:[1,0]
	v_pk_fma_f32 v[104:105], v[96:97], v[104:105], v[94:95] op_sel:[0,1,0] op_sel_hi:[1,0,0]
	v_pk_mul_f32 v[96:97], v[90:91], v[106:107]
	v_pk_fma_f32 v[90:91], v[90:91], v[106:107], v[114:115] op_sel_hi:[0,1,1]
	v_mul_f32_e32 v90, v93, v109
	v_pk_fma_f32 v[106:107], v[92:93], v[108:109], v[90:91] op_sel_hi:[1,1,0] neg_lo:[0,0,1] neg_hi:[0,0,1]
	v_mul_f32_e32 v90, v93, v108
	v_pk_fma_f32 v[108:109], v[92:93], v[108:109], v[90:91] op_sel:[0,1,0] op_sel_hi:[1,0,0]
	v_sub_f32_e32 v94, v110, v112
	v_sub_f32_e32 v90, v96, v114
	v_mov_b32_e32 v96, v102
	v_mov_b32_e32 v97, v104
	v_mov_b32_e32 v92, v106
	v_mov_b32_e32 v93, v108
; __device__ __forceinline__ unsigned pk2(float lo, float hi) { f32x2 v = {lo, hi}; bf16x2_t b = __builtin_convertvector(v, bf16x2_t); return __builtin_bit_cast(unsigned, b); }
;     __device__ __forceinline__ void operator()(AccT& acc, const Unit& u, int wr, int wc, int fr, int fq) const {
;     ...
;             for (int m = 0; m < 4; ++m) { const int row = row0 + ai * HALF + m * 16; bf16_t* rowp = Q + (size_t)row * (NH * DQK) + col0;
;                 const float r = rsq[row] * QSCALE; const int pos = row & (SEQ - 1);
; #pragma unroll
;                 for (int bj = 0; bj < 2; ++bj) { f32x4 v0 = acc[ai][bj][m][0], v1 = acc[ai][bj][m][1];
;                     const int cl = (col0 + bj * HALF) % DQK;
;                     if (cl >= DN) { const f32x4* cp = (const f32x4*)(cs + (size_t)pos * 32 + ((cl - DN) >> 1)); const f32x4 c0 = cp[0], c1 = cp[1];
;                         f32x4 t0, t1;
;                         t0[0] = v0[0] * c0[0] - v0[1] * c0[1]; t0[1] = v0[0] * c0[1] + v0[1] * c0[0];
;                         t0[2] = v0[2] * c0[2] - v0[3] * c0[3]; t0[3] = v0[2] * c0[3] + v0[3] * c0[2];
;                         t1[0] = v1[0] * c1[0] - v1[1] * c1[1]; t1[1] = v1[0] * c1[1] + v1[1] * c1[0];
;                         t1[2] = v1[2] * c1[2] - v1[3] * c1[3]; t1[3] = v1[2] * c1[3] + v1[3] * c1[2];
;                         v0 = t0; v1 = t1; }
;                     v0 = v0 * r; v1 = v1 * r;
;                     u32x4 w; w.x = pk2(v0[0], v0[1]); w.y = pk2(v0[2], v0[3]); w.z = pk2(v1[0], v1[1]); w.w = pk2(v1[2], v1[3]);
;                     *(u32x4*)(rowp + bj * HALF) = w; } }
.LBB0_122:
	s_or_b64 exec, exec, s[2:3]
	v_mov_b64_e32 v[102:103], s[16:17]
	v_mov_b32_e32 v100, v170
	v_mul_f32_e32 v100, 0x3dd53b94, v100
	v_mad_i64_i32 v[98:99], s[2:3], v98, s8, v[102:103]
	v_pk_mul_f32 v[96:97], v[100:101], v[96:97] op_sel_hi:[0,1]
	v_pk_mul_f32 v[94:95], v[100:101], v[94:95] op_sel_hi:[0,1]
	v_pk_mul_f32 v[102:103], v[100:101], v[92:93] op_sel_hi:[0,1]
	v_pk_mul_f32 v[92:93], v[100:101], v[90:91] op_sel_hi:[0,1]
	v_lshl_add_u64 v[98:99], v[142:143], 1, v[98:99]
	v_cvt_pk_bf16_f32 v90, v94, v95
	v_cvt_pk_bf16_f32 v91, v96, v97
	v_cvt_pk_bf16_f32 v92, v92, v93
	v_cvt_pk_bf16_f32 v93, v102, v103
	flat_store_dwordx4 v[98:99], v[90:93]
	s_and_saveexec_b64 s[2:3], s[0:1]
	s_cbranch_execz .LBB0_124
	v_lshl_add_u64 v[90:91], s[24:25], 0, v[0:1]
	v_mov_b32_e32 v123, v1
	v_lshl_add_u64 v[94:95], v[122:123], 3, v[90:91]
	s_nop 0
	v_mov_b32_e32 v90, v198
	v_mov_b32_e32 v91, v199
	v_mov_b32_e32 v92, v200
	v_mov_b32_e32 v93, v201
	v_mov_b32_e32 v94, v212
	v_mov_b32_e32 v95, v213
	v_mov_b32_e32 v96, v214
	v_mov_b32_e32 v97, v215
	v_pk_mul_f32 v[104:105], v[86:87], v[90:91] op_sel:[1,1] op_sel_hi:[1,0]
	v_mul_f32_e32 v0, v89, v93
	v_pk_mul_f32 v[102:103], v[86:87], v[90:91]
	v_pk_fma_f32 v[86:87], v[86:87], v[90:91], v[104:105] op_sel_hi:[0,1,1]
	v_pk_fma_f32 v[90:91], v[88:89], v[92:93], v[0:1] op_sel_hi:[1,1,0] neg_lo:[0,0,1] neg_hi:[0,0,1]
	v_mul_f32_e32 v0, v89, v92
	v_pk_fma_f32 v[92:93], v[88:89], v[92:93], v[0:1] op_sel:[0,1,0] op_sel_hi:[1,0,0]
	v_pk_mul_f32 v[106:107], v[82:83], v[94:95] op_sel:[1,1] op_sel_hi:[1,0]
	v_mul_f32_e32 v0, v85, v97
	v_pk_mul_f32 v[88:89], v[82:83], v[94:95]
	v_pk_fma_f32 v[82:83], v[82:83], v[94:95], v[106:107] op_sel_hi:[0,1,1]
	v_pk_fma_f32 v[94:95], v[84:85], v[96:97], v[0:1] op_sel_hi:[1,1,0] neg_lo:[0,0,1] neg_hi:[0,0,1]
	v_mul_f32_e32 v0, v85, v96
	v_pk_fma_f32 v[96:97], v[84:85], v[96:97], v[0:1] op_sel:[0,1,0] op_sel_hi:[1,0,0]
	v_sub_f32_e32 v86, v102, v104
	v_sub_f32_e32 v82, v88, v106
	v_mov_b32_e32 v88, v90
	v_mov_b32_e32 v89, v92
	v_mov_b32_e32 v84, v94
	v_mov_b32_e32 v85, v96
.LBB0_124:
	s_or_b64 exec, exec, s[2:3]
	v_mov_b32_e32 v101, v100
	v_mov_b32_e32 v90, v100
	v_mov_b32_e32 v91, v100
	v_pk_mul_f32 v[88:89], v[90:91], v[88:89]
	v_pk_mul_f32 v[86:87], v[100:101], v[86:87]
	v_pk_mul_f32 v[90:91], v[90:91], v[84:85]
	v_pk_mul_f32 v[84:85], v[100:101], v[82:83]
	v_cvt_pk_bf16_f32 v82, v86, v87
	v_cvt_pk_bf16_f32 v83, v88, v89
	v_cvt_pk_bf16_f32 v84, v84, v85
	v_cvt_pk_bf16_f32 v85, v90, v91
	flat_store_dwordx4 v[98:99], v[82:85] offset:256
	s_nop 1
	v_or_b32_e32 v82, 48, v146
	v_ashrrev_i32_e32 v83, 31, v82
	v_lshl_add_u64 v[84:85], v[82:83], 2, s[18:19]
	s_nop 0
	v_lshlrev_b32_e32 v0, 5, v82
	v_and_b32_e32 v0, 0x1ffe0, v0
	v_lshlrev_b32_e32 v0, 3, v0
	s_and_saveexec_b64 s[2:3], vcc
	s_cbranch_execz .LBB0_126
	v_lshl_add_u64 v[86:87], s[24:25], 0, v[0:1]
	v_mov_b32_e32 v145, v1
	v_lshl_add_u64 v[90:91], v[144:145], 3, v[86:87]
	s_nop 0
	v_mov_b32_e32 v86, v216
	v_mov_b32_e32 v87, v217
	v_mov_b32_e32 v88, v218
	v_mov_b32_e32 v89, v219
	v_mov_b32_e32 v90, v220
	v_mov_b32_e32 v91, v221
	v_mov_b32_e32 v92, v222
	v_mov_b32_e32 v93, v223
	v_pk_mul_f32 v[96:97], v[78:79], v[86:87] op_sel:[1,1] op_sel_hi:[1,0]
	v_pk_mul_f32 v[94:95], v[78:79], v[86:87]
	v_pk_fma_f32 v[78:79], v[78:79], v[86:87], v[96:97] op_sel_hi:[0,1,1]
	v_mul_f32_e32 v78, v81, v89
	v_pk_fma_f32 v[86:87], v[80:81], v[88:89], v[78:79] op_sel_hi:[1,1,0] neg_lo:[0,0,1] neg_hi:[0,0,1]
	v_mul_f32_e32 v78, v81, v88
	v_pk_mul_f32 v[98:99], v[74:75], v[90:91] op_sel:[1,1] op_sel_hi:[1,0]
	v_pk_fma_f32 v[88:89], v[80:81], v[88:89], v[78:79] op_sel:[0,1,0] op_sel_hi:[1,0,0]
	v_pk_mul_f32 v[80:81], v[74:75], v[90:91]
	v_pk_fma_f32 v[74:75], v[74:75], v[90:91], v[98:99] op_sel_hi:[0,1,1]
	v_mul_f32_e32 v74, v77, v93
	v_pk_fma_f32 v[90:91], v[76:77], v[92:93], v[74:75] op_sel_hi:[1,1,0] neg_lo:[0,0,1] neg_hi:[0,0,1]
	v_mul_f32_e32 v74, v77, v92
	v_pk_fma_f32 v[92:93], v[76:77], v[92:93], v[74:75] op_sel:[0,1,0] op_sel_hi:[1,0,0]
	v_sub_f32_e32 v78, v94, v96
	v_sub_f32_e32 v74, v80, v98
	v_mov_b32_e32 v80, v86
	v_mov_b32_e32 v81, v88
	v_mov_b32_e32 v76, v90
	v_mov_b32_e32 v77, v92
.LBB0_126:
	s_or_b64 exec, exec, s[2:3]
	v_mov_b64_e32 v[86:87], s[16:17]
	v_mov_b32_e32 v84, v171
	v_mul_f32_e32 v84, 0x3dd53b94, v84
	v_mad_i64_i32 v[82:83], s[2:3], v82, s8, v[86:87]
	v_pk_mul_f32 v[80:81], v[84:85], v[80:81] op_sel_hi:[0,1]
	v_pk_mul_f32 v[78:79], v[84:85], v[78:79] op_sel_hi:[0,1]
	v_pk_mul_f32 v[86:87], v[84:85], v[76:77] op_sel_hi:[0,1]
	v_pk_mul_f32 v[76:77], v[84:85], v[74:75] op_sel_hi:[0,1]
	v_lshl_add_u64 v[82:83], v[142:143], 1, v[82:83]
	v_cvt_pk_bf16_f32 v74, v78, v79
	v_cvt_pk_bf16_f32 v75, v80, v81
	v_cvt_pk_bf16_f32 v76, v76, v77
	v_cvt_pk_bf16_f32 v77, v86, v87
	flat_store_dwordx4 v[82:83], v[74:77]
	s_and_saveexec_b64 s[2:3], s[0:1]
	s_cbranch_execz .LBB0_128
	v_lshl_add_u64 v[74:75], s[24:25], 0, v[0:1]
	v_mov_b32_e32 v123, v1
	v_lshl_add_u64 v[78:79], v[122:123], 3, v[74:75]
	s_nop 0
	v_mov_b32_e32 v74, v216
	v_mov_b32_e32 v75, v217
	v_mov_b32_e32 v76, v218
	v_mov_b32_e32 v77, v219
	v_mov_b32_e32 v78, v220
	v_mov_b32_e32 v79, v221
	v_mov_b32_e32 v80, v222
	v_mov_b32_e32 v81, v223
	v_pk_mul_f32 v[88:89], v[70:71], v[74:75] op_sel:[1,1] op_sel_hi:[1,0]
	v_mul_f32_e32 v0, v73, v77
	v_pk_mul_f32 v[86:87], v[70:71], v[74:75]
	v_pk_fma_f32 v[70:71], v[70:71], v[74:75], v[88:89] op_sel_hi:[0,1,1]
	v_pk_fma_f32 v[74:75], v[72:73], v[76:77], v[0:1] op_sel_hi:[1,1,0] neg_lo:[0,0,1] neg_hi:[0,0,1]
	v_mul_f32_e32 v0, v73, v76
	v_pk_fma_f32 v[76:77], v[72:73], v[76:77], v[0:1] op_sel:[0,1,0] op_sel_hi:[1,0,0]
	v_pk_mul_f32 v[90:91], v[66:67], v[78:79] op_sel:[1,1] op_sel_hi:[1,0]
	v_mul_f32_e32 v0, v69, v81
	v_pk_mul_f32 v[72:73], v[66:67], v[78:79]
	v_pk_fma_f32 v[66:67], v[66:67], v[78:79], v[90:91] op_sel_hi:[0,1,1]
	v_pk_fma_f32 v[78:79], v[68:69], v[80:81], v[0:1] op_sel_hi:[1,1,0] neg_lo:[0,0,1] neg_hi:[0,0,1]
	v_mul_f32_e32 v0, v69, v80
	v_pk_fma_f32 v[80:81], v[68:69], v[80:81], v[0:1] op_sel:[0,1,0] op_sel_hi:[1,0,0]
	v_sub_f32_e32 v70, v86, v88
	v_sub_f32_e32 v66, v72, v90
	v_mov_b32_e32 v72, v74
	v_mov_b32_e32 v73, v76
	v_mov_b32_e32 v68, v78
	v_mov_b32_e32 v69, v80
; __device__ __forceinline__ unsigned pk2(float lo, float hi) { f32x2 v = {lo, hi}; bf16x2_t b = __builtin_convertvector(v, bf16x2_t); return __builtin_bit_cast(unsigned, b); }
;     __device__ __forceinline__ void operator()(AccT& acc, const Unit& u, int wr, int wc, int fr, int fq) const {
;     ...
; #pragma unroll
;         for (int ai = 0; ai < 2; ++ai)
; #pragma unroll
;             for (int m = 0; m < 4; ++m) { const int row = row0 + ai * HALF + m * 16; bf16_t* rowp = Q + (size_t)row * (NH * DQK) + col0;
;                 const float r = rsq[row] * QSCALE; const int pos = row & (SEQ - 1);
; #pragma unroll
;                 for (int bj = 0; bj < 2; ++bj) { f32x4 v0 = acc[ai][bj][m][0], v1 = acc[ai][bj][m][1];
;                     const int cl = (col0 + bj * HALF) % DQK;
;                     if (cl >= DN) { const f32x4* cp = (const f32x4*)(cs + (size_t)pos * 32 + ((cl - DN) >> 1)); const f32x4 c0 = cp[0], c1 = cp[1];
;                         f32x4 t0, t1;
;                         t0[0] = v0[0] * c0[0] - v0[1] * c0[1]; t0[1] = v0[0] * c0[1] + v0[1] * c0[0];
;                         t0[2] = v0[2] * c0[2] - v0[3] * c0[3]; t0[3] = v0[2] * c0[3] + v0[3] * c0[2];
;                         t1[0] = v1[0] * c1[0] - v1[1] * c1[1]; t1[1] = v1[0] * c1[1] + v1[1] * c1[0];
;                         t1[2] = v1[2] * c1[2] - v1[3] * c1[3]; t1[3] = v1[2] * c1[3] + v1[3] * c1[2];
;                         v0 = t0; v1 = t1; }
;                     v0 = v0 * r; v1 = v1 * r;
;                     u32x4 w; w.x = pk2(v0[0], v0[1]); w.y = pk2(v0[2], v0[3]); w.z = pk2(v1[0], v1[1]); w.w = pk2(v1[2], v1[3]);
;                     *(u32x4*)(rowp + bj * HALF) = w; } }
.LBB0_128:
	s_or_b64 exec, exec, s[2:3]
	v_mov_b32_e32 v85, v84
	v_mov_b32_e32 v74, v84
	v_mov_b32_e32 v75, v84
	v_pk_mul_f32 v[72:73], v[74:75], v[72:73]
	v_pk_mul_f32 v[70:71], v[84:85], v[70:71]
	v_pk_mul_f32 v[74:75], v[74:75], v[68:69]
	v_pk_mul_f32 v[68:69], v[84:85], v[66:67]
	v_cvt_pk_bf16_f32 v66, v70, v71
	v_cvt_pk_bf16_f32 v67, v72, v73
	v_cvt_pk_bf16_f32 v68, v68, v69
	v_cvt_pk_bf16_f32 v69, v74, v75
	flat_store_dwordx4 v[82:83], v[66:69] offset:256
	s_mov_b64 exec, s[100:101]
	s_cbranch_execz .Lq_mid_skip
	v_add_u32_e32 v253, 0x8000, v252
	global_load_dwordx4 v[176:179], v253, s[24:25]
	global_load_dwordx4 v[180:183], v253, s[24:25] offset:16
	v_add_u32_e32 v254, 0x9000, v252
	global_load_dwordx4 v[184:187], v254, s[24:25]
	global_load_dwordx4 v[188:191], v254, s[24:25] offset:16
	v_add_u32_e32 v255, 0xa000, v252
	global_load_dwordx4 v[198:201], v255, s[24:25]
	global_load_dwordx4 v[212:215], v255, s[24:25] offset:16
	v_add_u32_e32 v253, 0xb000, v252
	global_load_dwordx4 v[216:219], v253, s[24:25]
	global_load_dwordx4 v[220:223], v253, s[24:25] offset:16
.Lq_mid_skip:
	s_mov_b64 exec, -1
	s_waitcnt vmcnt(0)
	s_nop 0
	s_nop 0
	v_add_u32_e32 v66, 0x80, v146
	v_lshlrev_b32_e32 v0, 5, v66
	v_and_b32_e32 v0, 0x1f9e0, v0
	v_lshlrev_b32_e32 v0, 3, v0
	s_and_saveexec_b64 s[2:3], vcc
	s_cbranch_execz .LBB0_130
	v_lshl_add_u64 v[70:71], s[24:25], 0, v[0:1]
	v_mov_b32_e32 v145, v1
	v_lshl_add_u64 v[74:75], v[144:145], 3, v[70:71]
	s_nop 0
	v_mov_b32_e32 v70, v176
	v_mov_b32_e32 v71, v177
	v_mov_b32_e32 v72, v178
	v_mov_b32_e32 v73, v179
	v_mov_b32_e32 v74, v180
	v_mov_b32_e32 v75, v181
	v_mov_b32_e32 v76, v182
	v_mov_b32_e32 v77, v183
	v_pk_mul_f32 v[80:81], v[62:63], v[70:71] op_sel:[1,1] op_sel_hi:[1,0]
	v_pk_mul_f32 v[78:79], v[62:63], v[70:71]
	v_pk_fma_f32 v[62:63], v[62:63], v[70:71], v[80:81] op_sel_hi:[0,1,1]
	v_mul_f32_e32 v62, v65, v73
	v_pk_fma_f32 v[70:71], v[64:65], v[72:73], v[62:63] op_sel_hi:[1,1,0] neg_lo:[0,0,1] neg_hi:[0,0,1]
	v_mul_f32_e32 v62, v65, v72
	v_pk_mul_f32 v[82:83], v[58:59], v[74:75] op_sel:[1,1] op_sel_hi:[1,0]
	v_pk_fma_f32 v[72:73], v[64:65], v[72:73], v[62:63] op_sel:[0,1,0] op_sel_hi:[1,0,0]
	v_pk_mul_f32 v[64:65], v[58:59], v[74:75]
	v_pk_fma_f32 v[58:59], v[58:59], v[74:75], v[82:83] op_sel_hi:[0,1,1]
	v_mul_f32_e32 v58, v61, v77
	v_pk_fma_f32 v[74:75], v[60:61], v[76:77], v[58:59] op_sel_hi:[1,1,0] neg_lo:[0,0,1] neg_hi:[0,0,1]
	v_mul_f32_e32 v58, v61, v76
	v_pk_fma_f32 v[76:77], v[60:61], v[76:77], v[58:59] op_sel:[0,1,0] op_sel_hi:[1,0,0]
	v_sub_f32_e32 v62, v78, v80
	v_sub_f32_e32 v58, v64, v82
	v_mov_b32_e32 v64, v70
	v_mov_b32_e32 v65, v72
	v_mov_b32_e32 v60, v74
	v_mov_b32_e32 v61, v76
.LBB0_130:
	s_or_b64 exec, exec, s[2:3]
	v_mov_b64_e32 v[70:71], s[16:17]
	v_mov_b32_e32 v68, v172
	v_mul_f32_e32 v68, 0x3dd53b94, v68
	v_mad_i64_i32 v[66:67], s[2:3], v66, s8, v[70:71]
	v_pk_mul_f32 v[64:65], v[68:69], v[64:65] op_sel_hi:[0,1]
	v_pk_mul_f32 v[62:63], v[68:69], v[62:63] op_sel_hi:[0,1]
	v_pk_mul_f32 v[70:71], v[68:69], v[60:61] op_sel_hi:[0,1]
	v_pk_mul_f32 v[60:61], v[68:69], v[58:59] op_sel_hi:[0,1]
	v_lshl_add_u64 v[66:67], v[142:143], 1, v[66:67]
	v_cvt_pk_bf16_f32 v58, v62, v63
	v_cvt_pk_bf16_f32 v59, v64, v65
	v_cvt_pk_bf16_f32 v60, v60, v61
	v_cvt_pk_bf16_f32 v61, v70, v71
	flat_store_dwordx4 v[66:67], v[58:61]
	s_and_saveexec_b64 s[2:3], s[0:1]
	s_cbranch_execz .LBB0_132
	v_lshl_add_u64 v[58:59], s[24:25], 0, v[0:1]
	v_mov_b32_e32 v123, v1
	v_lshl_add_u64 v[62:63], v[122:123], 3, v[58:59]
	s_nop 0
	v_mov_b32_e32 v58, v176
	v_mov_b32_e32 v59, v177
	v_mov_b32_e32 v60, v178
	v_mov_b32_e32 v61, v179
	v_mov_b32_e32 v62, v180
	v_mov_b32_e32 v63, v181
	v_mov_b32_e32 v64, v182
	v_mov_b32_e32 v65, v183
	v_pk_mul_f32 v[72:73], v[54:55], v[58:59] op_sel:[1,1] op_sel_hi:[1,0]
	v_mul_f32_e32 v0, v57, v61
	v_pk_mul_f32 v[70:71], v[54:55], v[58:59]
	v_pk_fma_f32 v[54:55], v[54:55], v[58:59], v[72:73] op_sel_hi:[0,1,1]
	v_pk_fma_f32 v[58:59], v[56:57], v[60:61], v[0:1] op_sel_hi:[1,1,0] neg_lo:[0,0,1] neg_hi:[0,0,1]
	v_mul_f32_e32 v0, v57, v60
	v_pk_fma_f32 v[60:61], v[56:57], v[60:61], v[0:1] op_sel:[0,1,0] op_sel_hi:[1,0,0]
	v_pk_mul_f32 v[74:75], v[50:51], v[62:63] op_sel:[1,1] op_sel_hi:[1,0]
	v_mul_f32_e32 v0, v53, v65
	v_pk_mul_f32 v[56:57], v[50:51], v[62:63]
	v_pk_fma_f32 v[50:51], v[50:51], v[62:63], v[74:75] op_sel_hi:[0,1,1]
	v_pk_fma_f32 v[62:63], v[52:53], v[64:65], v[0:1] op_sel_hi:[1,1,0] neg_lo:[0,0,1] neg_hi:[0,0,1]
	v_mul_f32_e32 v0, v53, v64
	v_pk_fma_f32 v[64:65], v[52:53], v[64:65], v[0:1] op_sel:[0,1,0] op_sel_hi:[1,0,0]
	v_sub_f32_e32 v54, v70, v72
	v_sub_f32_e32 v50, v56, v74
	v_mov_b32_e32 v56, v58
	v_mov_b32_e32 v57, v60
	v_mov_b32_e32 v52, v62
	v_mov_b32_e32 v53, v64
; __device__ __forceinline__ unsigned pk2(float lo, float hi) { f32x2 v = {lo, hi}; bf16x2_t b = __builtin_convertvector(v, bf16x2_t); return __builtin_bit_cast(unsigned, b); }
;     __device__ __forceinline__ void operator()(AccT& acc, const Unit& u, int wr, int wc, int fr, int fq) const {
;     ...
;             for (int m = 0; m < 4; ++m) { const int row = row0 + ai * HALF + m * 16; bf16_t* rowp = Q + (size_t)row * (NH * DQK) + col0;
;                 const float r = rsq[row] * QSCALE; const int pos = row & (SEQ - 1);
; #pragma unroll
;                 for (int bj = 0; bj < 2; ++bj) { f32x4 v0 = acc[ai][bj][m][0], v1 = acc[ai][bj][m][1];
;                     const int cl = (col0 + bj * HALF) % DQK;
;                     if (cl >= DN) { const f32x4* cp = (const f32x4*)(cs + (size_t)pos * 32 + ((cl - DN) >> 1)); const f32x4 c0 = cp[0], c1 = cp[1];
;                         f32x4 t0, t1;
;                         t0[0] = v0[0] * c0[0] - v0[1] * c0[1]; t0[1] = v0[0] * c0[1] + v0[1] * c0[0];
;                         t0[2] = v0[2] * c0[2] - v0[3] * c0[3]; t0[3] = v0[2] * c0[3] + v0[3] * c0[2];
;                         t1[0] = v1[0] * c1[0] - v1[1] * c1[1]; t1[1] = v1[0] * c1[1] + v1[1] * c1[0];
;                         t1[2] = v1[2] * c1[2] - v1[3] * c1[3]; t1[3] = v1[2] * c1[3] + v1[3] * c1[2];
;                         v0 = t0; v1 = t1; }
;                     v0 = v0 * r; v1 = v1 * r;
;                     u32x4 w; w.x = pk2(v0[0], v0[1]); w.y = pk2(v0[2], v0[3]); w.z = pk2(v1[0], v1[1]); w.w = pk2(v1[2], v1[3]);
;                     *(u32x4*)(rowp + bj * HALF) = w; } }
.LBB0_132:
	s_or_b64 exec, exec, s[2:3]
	v_mov_b32_e32 v69, v68
	v_mov_b32_e32 v58, v68
	v_mov_b32_e32 v59, v68
	v_pk_mul_f32 v[56:57], v[58:59], v[56:57]
	v_pk_mul_f32 v[54:55], v[68:69], v[54:55]
	v_pk_mul_f32 v[58:59], v[58:59], v[52:53]
	v_pk_mul_f32 v[52:53], v[68:69], v[50:51]
	v_cvt_pk_bf16_f32 v50, v54, v55
	v_cvt_pk_bf16_f32 v51, v56, v57
	v_cvt_pk_bf16_f32 v52, v52, v53
	v_cvt_pk_bf16_f32 v53, v58, v59
	flat_store_dwordx4 v[66:67], v[50:53] offset:256
	s_nop 0
	s_nop 0
	v_add_u32_e32 v50, 0x90, v146
	v_lshlrev_b32_e32 v0, 5, v50
	v_and_b32_e32 v0, 0x1fbe0, v0
	v_lshlrev_b32_e32 v0, 3, v0
	s_and_saveexec_b64 s[2:3], vcc
	s_cbranch_execz .LBB0_134
	v_lshl_add_u64 v[54:55], s[24:25], 0, v[0:1]
	v_mov_b32_e32 v145, v1
	v_lshl_add_u64 v[58:59], v[144:145], 3, v[54:55]
	s_nop 0
	v_mov_b32_e32 v54, v184
	v_mov_b32_e32 v55, v185
	v_mov_b32_e32 v56, v186
	v_mov_b32_e32 v57, v187
	v_mov_b32_e32 v58, v188
	v_mov_b32_e32 v59, v189
	v_mov_b32_e32 v60, v190
	v_mov_b32_e32 v61, v191
	v_pk_mul_f32 v[64:65], v[46:47], v[54:55] op_sel:[1,1] op_sel_hi:[1,0]
	v_pk_mul_f32 v[62:63], v[46:47], v[54:55]
	v_pk_fma_f32 v[46:47], v[46:47], v[54:55], v[64:65] op_sel_hi:[0,1,1]
	v_mul_f32_e32 v46, v49, v57
	v_pk_fma_f32 v[54:55], v[48:49], v[56:57], v[46:47] op_sel_hi:[1,1,0] neg_lo:[0,0,1] neg_hi:[0,0,1]
	v_mul_f32_e32 v46, v49, v56
	v_pk_mul_f32 v[66:67], v[42:43], v[58:59] op_sel:[1,1] op_sel_hi:[1,0]
	v_pk_fma_f32 v[56:57], v[48:49], v[56:57], v[46:47] op_sel:[0,1,0] op_sel_hi:[1,0,0]
	v_pk_mul_f32 v[48:49], v[42:43], v[58:59]
	v_pk_fma_f32 v[42:43], v[42:43], v[58:59], v[66:67] op_sel_hi:[0,1,1]
	v_mul_f32_e32 v42, v45, v61
	v_pk_fma_f32 v[58:59], v[44:45], v[60:61], v[42:43] op_sel_hi:[1,1,0] neg_lo:[0,0,1] neg_hi:[0,0,1]
	v_mul_f32_e32 v42, v45, v60
	v_pk_fma_f32 v[60:61], v[44:45], v[60:61], v[42:43] op_sel:[0,1,0] op_sel_hi:[1,0,0]
	v_sub_f32_e32 v46, v62, v64
	v_sub_f32_e32 v42, v48, v66
	v_mov_b32_e32 v48, v54
	v_mov_b32_e32 v49, v56
	v_mov_b32_e32 v44, v58
	v_mov_b32_e32 v45, v60
.LBB0_134:
	s_or_b64 exec, exec, s[2:3]
	v_mov_b64_e32 v[54:55], s[16:17]
	v_mov_b32_e32 v52, v173
	v_mul_f32_e32 v52, 0x3dd53b94, v52
	v_mad_i64_i32 v[50:51], s[2:3], v50, s8, v[54:55]
	v_pk_mul_f32 v[48:49], v[52:53], v[48:49] op_sel_hi:[0,1]
	v_pk_mul_f32 v[46:47], v[52:53], v[46:47] op_sel_hi:[0,1]
	v_pk_mul_f32 v[54:55], v[52:53], v[44:45] op_sel_hi:[0,1]
	v_pk_mul_f32 v[44:45], v[52:53], v[42:43] op_sel_hi:[0,1]
	v_lshl_add_u64 v[50:51], v[142:143], 1, v[50:51]
	v_cvt_pk_bf16_f32 v42, v46, v47
	v_cvt_pk_bf16_f32 v43, v48, v49
	v_cvt_pk_bf16_f32 v44, v44, v45
	v_cvt_pk_bf16_f32 v45, v54, v55
	flat_store_dwordx4 v[50:51], v[42:45]
	s_and_saveexec_b64 s[2:3], s[0:1]
	s_cbranch_execz .LBB0_136
	v_lshl_add_u64 v[42:43], s[24:25], 0, v[0:1]
	v_mov_b32_e32 v123, v1
	v_lshl_add_u64 v[46:47], v[122:123], 3, v[42:43]
	s_nop 0
	v_mov_b32_e32 v42, v184
	v_mov_b32_e32 v43, v185
	v_mov_b32_e32 v44, v186
	v_mov_b32_e32 v45, v187
	v_mov_b32_e32 v46, v188
	v_mov_b32_e32 v47, v189
	v_mov_b32_e32 v48, v190
	v_mov_b32_e32 v49, v191
	v_pk_mul_f32 v[56:57], v[38:39], v[42:43] op_sel:[1,1] op_sel_hi:[1,0]
	v_mul_f32_e32 v0, v41, v45
	v_pk_mul_f32 v[54:55], v[38:39], v[42:43]
	v_pk_fma_f32 v[38:39], v[38:39], v[42:43], v[56:57] op_sel_hi:[0,1,1]
	v_pk_fma_f32 v[42:43], v[40:41], v[44:45], v[0:1] op_sel_hi:[1,1,0] neg_lo:[0,0,1] neg_hi:[0,0,1]
	v_mul_f32_e32 v0, v41, v44
	v_pk_fma_f32 v[44:45], v[40:41], v[44:45], v[0:1] op_sel:[0,1,0] op_sel_hi:[1,0,0]
	v_pk_mul_f32 v[58:59], v[34:35], v[46:47] op_sel:[1,1] op_sel_hi:[1,0]
	v_mul_f32_e32 v0, v37, v49
	v_pk_mul_f32 v[40:41], v[34:35], v[46:47]
	v_pk_fma_f32 v[34:35], v[34:35], v[46:47], v[58:59] op_sel_hi:[0,1,1]
	v_pk_fma_f32 v[46:47], v[36:37], v[48:49], v[0:1] op_sel_hi:[1,1,0] neg_lo:[0,0,1] neg_hi:[0,0,1]
	v_mul_f32_e32 v0, v37, v48
	v_pk_fma_f32 v[48:49], v[36:37], v[48:49], v[0:1] op_sel:[0,1,0] op_sel_hi:[1,0,0]
	v_sub_f32_e32 v38, v54, v56
	v_sub_f32_e32 v34, v40, v58
	v_mov_b32_e32 v40, v42
	v_mov_b32_e32 v41, v44
	v_mov_b32_e32 v36, v46
	v_mov_b32_e32 v37, v48
.LBB0_136:
	s_or_b64 exec, exec, s[2:3]
	v_mov_b32_e32 v53, v52
	v_mov_b32_e32 v42, v52
	v_mov_b32_e32 v43, v52
	v_pk_mul_f32 v[40:41], v[42:43], v[40:41]
	v_pk_mul_f32 v[38:39], v[52:53], v[38:39]
	v_pk_mul_f32 v[42:43], v[42:43], v[36:37]
	v_pk_mul_f32 v[36:37], v[52:53], v[34:35]
	v_cvt_pk_bf16_f32 v34, v38, v39
	v_cvt_pk_bf16_f32 v35, v40, v41
	v_cvt_pk_bf16_f32 v36, v36, v37
	v_cvt_pk_bf16_f32 v37, v42, v43
	flat_store_dwordx4 v[50:51], v[34:37] offset:256
	s_nop 0
	s_nop 0
	v_add_u32_e32 v34, 0xa0, v146
	v_lshlrev_b32_e32 v0, 5, v34
	v_and_b32_e32 v0, 0x1fde0, v0
	v_lshlrev_b32_e32 v0, 3, v0
	s_and_saveexec_b64 s[2:3], vcc
	s_cbranch_execz .LBB0_138
	v_lshl_add_u64 v[38:39], s[24:25], 0, v[0:1]
	v_mov_b32_e32 v145, v1
	v_lshl_add_u64 v[42:43], v[144:145], 3, v[38:39]
	s_nop 0
	v_mov_b32_e32 v38, v198
	v_mov_b32_e32 v39, v199
	v_mov_b32_e32 v40, v200
	v_mov_b32_e32 v41, v201
	v_mov_b32_e32 v42, v212
	v_mov_b32_e32 v43, v213
	v_mov_b32_e32 v44, v214
	v_mov_b32_e32 v45, v215
	v_pk_mul_f32 v[48:49], v[30:31], v[38:39] op_sel:[1,1] op_sel_hi:[1,0]
	v_pk_mul_f32 v[46:47], v[30:31], v[38:39]
	v_pk_fma_f32 v[30:31], v[30:31], v[38:39], v[48:49] op_sel_hi:[0,1,1]
	v_mul_f32_e32 v30, v33, v41
	v_pk_fma_f32 v[38:39], v[32:33], v[40:41], v[30:31] op_sel_hi:[1,1,0] neg_lo:[0,0,1] neg_hi:[0,0,1]
	v_mul_f32_e32 v30, v33, v40
	v_pk_mul_f32 v[50:51], v[26:27], v[42:43] op_sel:[1,1] op_sel_hi:[1,0]
	v_pk_fma_f32 v[40:41], v[32:33], v[40:41], v[30:31] op_sel:[0,1,0] op_sel_hi:[1,0,0]
	v_pk_mul_f32 v[32:33], v[26:27], v[42:43]
	v_pk_fma_f32 v[26:27], v[26:27], v[42:43], v[50:51] op_sel_hi:[0,1,1]
	v_mul_f32_e32 v26, v29, v45
	v_pk_fma_f32 v[42:43], v[28:29], v[44:45], v[26:27] op_sel_hi:[1,1,0] neg_lo:[0,0,1] neg_hi:[0,0,1]
	v_mul_f32_e32 v26, v29, v44
	v_pk_fma_f32 v[44:45], v[28:29], v[44:45], v[26:27] op_sel:[0,1,0] op_sel_hi:[1,0,0]
	v_sub_f32_e32 v30, v46, v48
	v_sub_f32_e32 v26, v32, v50
	v_mov_b32_e32 v32, v38
	v_mov_b32_e32 v33, v40
	v_mov_b32_e32 v28, v42
	v_mov_b32_e32 v29, v44
; __device__ __forceinline__ unsigned pk2(float lo, float hi) { f32x2 v = {lo, hi}; bf16x2_t b = __builtin_convertvector(v, bf16x2_t); return __builtin_bit_cast(unsigned, b); }
;     __device__ __forceinline__ void operator()(AccT& acc, const Unit& u, int wr, int wc, int fr, int fq) const {
;     ...
;             for (int m = 0; m < 4; ++m) { const int row = row0 + ai * HALF + m * 16; bf16_t* rowp = Q + (size_t)row * (NH * DQK) + col0;
;                 const float r = rsq[row] * QSCALE; const int pos = row & (SEQ - 1);
; #pragma unroll
;                 for (int bj = 0; bj < 2; ++bj) { f32x4 v0 = acc[ai][bj][m][0], v1 = acc[ai][bj][m][1];
;                     const int cl = (col0 + bj * HALF) % DQK;
;                     if (cl >= DN) { const f32x4* cp = (const f32x4*)(cs + (size_t)pos * 32 + ((cl - DN) >> 1)); const f32x4 c0 = cp[0], c1 = cp[1];
;                         f32x4 t0, t1;
;                         t0[0] = v0[0] * c0[0] - v0[1] * c0[1]; t0[1] = v0[0] * c0[1] + v0[1] * c0[0];
;                         t0[2] = v0[2] * c0[2] - v0[3] * c0[3]; t0[3] = v0[2] * c0[3] + v0[3] * c0[2];
;                         t1[0] = v1[0] * c1[0] - v1[1] * c1[1]; t1[1] = v1[0] * c1[1] + v1[1] * c1[0];
;                         t1[2] = v1[2] * c1[2] - v1[3] * c1[3]; t1[3] = v1[2] * c1[3] + v1[3] * c1[2];
;                         v0 = t0; v1 = t1; }
;                     v0 = v0 * r; v1 = v1 * r;
;                     u32x4 w; w.x = pk2(v0[0], v0[1]); w.y = pk2(v0[2], v0[3]); w.z = pk2(v1[0], v1[1]); w.w = pk2(v1[2], v1[3]);
;                     *(u32x4*)(rowp + bj * HALF) = w; } }
.LBB0_138:
	s_or_b64 exec, exec, s[2:3]
	v_mov_b64_e32 v[38:39], s[16:17]
	v_mov_b32_e32 v36, v174
	v_mul_f32_e32 v36, 0x3dd53b94, v36
	v_mad_i64_i32 v[34:35], s[2:3], v34, s8, v[38:39]
	v_pk_mul_f32 v[32:33], v[36:37], v[32:33] op_sel_hi:[0,1]
	v_pk_mul_f32 v[30:31], v[36:37], v[30:31] op_sel_hi:[0,1]
	v_pk_mul_f32 v[38:39], v[36:37], v[28:29] op_sel_hi:[0,1]
	v_pk_mul_f32 v[28:29], v[36:37], v[26:27] op_sel_hi:[0,1]
	v_lshl_add_u64 v[34:35], v[142:143], 1, v[34:35]
	v_cvt_pk_bf16_f32 v26, v30, v31
	v_cvt_pk_bf16_f32 v27, v32, v33
	v_cvt_pk_bf16_f32 v28, v28, v29
	v_cvt_pk_bf16_f32 v29, v38, v39
	flat_store_dwordx4 v[34:35], v[26:29]
	s_and_saveexec_b64 s[2:3], s[0:1]
	s_cbranch_execz .LBB0_140
	v_lshl_add_u64 v[26:27], s[24:25], 0, v[0:1]
	v_mov_b32_e32 v123, v1
	v_lshl_add_u64 v[30:31], v[122:123], 3, v[26:27]
	s_nop 0
	v_mov_b32_e32 v26, v198
	v_mov_b32_e32 v27, v199
	v_mov_b32_e32 v28, v200
	v_mov_b32_e32 v29, v201
	v_mov_b32_e32 v30, v212
	v_mov_b32_e32 v31, v213
	v_mov_b32_e32 v32, v214
	v_mov_b32_e32 v33, v215
	v_pk_mul_f32 v[40:41], v[22:23], v[26:27] op_sel:[1,1] op_sel_hi:[1,0]
	v_mul_f32_e32 v0, v25, v29
	v_pk_mul_f32 v[38:39], v[22:23], v[26:27]
	v_pk_fma_f32 v[22:23], v[22:23], v[26:27], v[40:41] op_sel_hi:[0,1,1]
	v_pk_fma_f32 v[26:27], v[24:25], v[28:29], v[0:1] op_sel_hi:[1,1,0] neg_lo:[0,0,1] neg_hi:[0,0,1]
	v_mul_f32_e32 v0, v25, v28
	v_pk_fma_f32 v[28:29], v[24:25], v[28:29], v[0:1] op_sel:[0,1,0] op_sel_hi:[1,0,0]
	v_pk_mul_f32 v[42:43], v[18:19], v[30:31] op_sel:[1,1] op_sel_hi:[1,0]
	v_mul_f32_e32 v0, v21, v33
	v_pk_mul_f32 v[24:25], v[18:19], v[30:31]
	v_pk_fma_f32 v[18:19], v[18:19], v[30:31], v[42:43] op_sel_hi:[0,1,1]
	v_pk_fma_f32 v[30:31], v[20:21], v[32:33], v[0:1] op_sel_hi:[1,1,0] neg_lo:[0,0,1] neg_hi:[0,0,1]
	v_mul_f32_e32 v0, v21, v32
	v_pk_fma_f32 v[32:33], v[20:21], v[32:33], v[0:1] op_sel:[0,1,0] op_sel_hi:[1,0,0]
	v_sub_f32_e32 v22, v38, v40
	v_sub_f32_e32 v18, v24, v42
	v_mov_b32_e32 v24, v26
	v_mov_b32_e32 v25, v28
	v_mov_b32_e32 v20, v30
	v_mov_b32_e32 v21, v32
.LBB0_140:
	s_or_b64 exec, exec, s[2:3]
	v_mov_b32_e32 v37, v36
	v_mov_b32_e32 v26, v36
	v_mov_b32_e32 v27, v36
	v_pk_mul_f32 v[24:25], v[26:27], v[24:25]
	v_pk_mul_f32 v[22:23], v[36:37], v[22:23]
	v_pk_mul_f32 v[26:27], v[26:27], v[20:21]
	v_pk_mul_f32 v[20:21], v[36:37], v[18:19]
	v_cvt_pk_bf16_f32 v18, v22, v23
	v_cvt_pk_bf16_f32 v19, v24, v25
	v_cvt_pk_bf16_f32 v20, v20, v21
	v_cvt_pk_bf16_f32 v21, v26, v27
	flat_store_dwordx4 v[34:35], v[18:21] offset:256
	s_nop 0
	s_nop 0
	v_add_u32_e32 v18, 0xb0, v146
	v_lshlrev_b32_e32 v0, 5, v18
	v_and_b32_e32 v0, 0x1ffe0, v0
	v_lshlrev_b32_e32 v0, 3, v0
	s_and_saveexec_b64 s[2:3], vcc
	s_cbranch_execz .LBB0_142
	v_lshl_add_u64 v[22:23], s[24:25], 0, v[0:1]
	v_mov_b32_e32 v145, v1
	v_lshl_add_u64 v[26:27], v[144:145], 3, v[22:23]
	s_nop 0
	v_mov_b32_e32 v22, v216
	v_mov_b32_e32 v23, v217
	v_mov_b32_e32 v24, v218
	v_mov_b32_e32 v25, v219
	v_mov_b32_e32 v26, v220
	v_mov_b32_e32 v27, v221
	v_mov_b32_e32 v28, v222
	v_mov_b32_e32 v29, v223
	v_pk_mul_f32 v[32:33], v[14:15], v[22:23] op_sel:[1,1] op_sel_hi:[1,0]
	v_pk_mul_f32 v[30:31], v[14:15], v[22:23]
	v_pk_fma_f32 v[14:15], v[14:15], v[22:23], v[32:33] op_sel_hi:[0,1,1]
	v_mul_f32_e32 v14, v17, v25
	v_pk_fma_f32 v[22:23], v[16:17], v[24:25], v[14:15] op_sel_hi:[1,1,0] neg_lo:[0,0,1] neg_hi:[0,0,1]
	v_mul_f32_e32 v14, v17, v24
	v_pk_mul_f32 v[34:35], v[10:11], v[26:27] op_sel:[1,1] op_sel_hi:[1,0]
	v_pk_fma_f32 v[24:25], v[16:17], v[24:25], v[14:15] op_sel:[0,1,0] op_sel_hi:[1,0,0]
	v_pk_mul_f32 v[16:17], v[10:11], v[26:27]
	v_pk_fma_f32 v[10:11], v[10:11], v[26:27], v[34:35] op_sel_hi:[0,1,1]
	v_mul_f32_e32 v10, v13, v29
	v_pk_fma_f32 v[26:27], v[12:13], v[28:29], v[10:11] op_sel_hi:[1,1,0] neg_lo:[0,0,1] neg_hi:[0,0,1]
	v_mul_f32_e32 v10, v13, v28
	v_pk_fma_f32 v[28:29], v[12:13], v[28:29], v[10:11] op_sel:[0,1,0] op_sel_hi:[1,0,0]
	v_sub_f32_e32 v14, v30, v32
	v_sub_f32_e32 v10, v16, v34
	v_mov_b32_e32 v16, v22
	v_mov_b32_e32 v17, v24
	v_mov_b32_e32 v12, v26
	v_mov_b32_e32 v13, v28
; __device__ __forceinline__ unsigned pk2(float lo, float hi) { f32x2 v = {lo, hi}; bf16x2_t b = __builtin_convertvector(v, bf16x2_t); return __builtin_bit_cast(unsigned, b); }
;     __device__ __forceinline__ void operator()(AccT& acc, const Unit& u, int wr, int wc, int fr, int fq) const {
;     ...
;             for (int m = 0; m < 4; ++m) { const int row = row0 + ai * HALF + m * 16; bf16_t* rowp = Q + (size_t)row * (NH * DQK) + col0;
;                 const float r = rsq[row] * QSCALE; const int pos = row & (SEQ - 1);
; #pragma unroll
;                 for (int bj = 0; bj < 2; ++bj) { f32x4 v0 = acc[ai][bj][m][0], v1 = acc[ai][bj][m][1];
;                     const int cl = (col0 + bj * HALF) % DQK;
;                     if (cl >= DN) { const f32x4* cp = (const f32x4*)(cs + (size_t)pos * 32 + ((cl - DN) >> 1)); const f32x4 c0 = cp[0], c1 = cp[1];
;                         f32x4 t0, t1;
;                         t0[0] = v0[0] * c0[0] - v0[1] * c0[1]; t0[1] = v0[0] * c0[1] + v0[1] * c0[0];
;                         t0[2] = v0[2] * c0[2] - v0[3] * c0[3]; t0[3] = v0[2] * c0[3] + v0[3] * c0[2];
;                         t1[0] = v1[0] * c1[0] - v1[1] * c1[1]; t1[1] = v1[0] * c1[1] + v1[1] * c1[0];
;                         t1[2] = v1[2] * c1[2] - v1[3] * c1[3]; t1[3] = v1[2] * c1[3] + v1[3] * c1[2];
;                         v0 = t0; v1 = t1; }
;                     v0 = v0 * r; v1 = v1 * r;
;                     u32x4 w; w.x = pk2(v0[0], v0[1]); w.y = pk2(v0[2], v0[3]); w.z = pk2(v1[0], v1[1]); w.w = pk2(v1[2], v1[3]);
;                     *(u32x4*)(rowp + bj * HALF) = w; } }
.LBB0_142:
	s_or_b64 exec, exec, s[2:3]
	v_mov_b64_e32 v[22:23], s[16:17]
	v_mov_b32_e32 v20, v175
	v_mul_f32_e32 v20, 0x3dd53b94, v20
	v_mad_i64_i32 v[18:19], s[2:3], v18, s8, v[22:23]
	v_pk_mul_f32 v[16:17], v[20:21], v[16:17] op_sel_hi:[0,1]
	v_pk_mul_f32 v[14:15], v[20:21], v[14:15] op_sel_hi:[0,1]
	v_pk_mul_f32 v[22:23], v[20:21], v[12:13] op_sel_hi:[0,1]
	v_pk_mul_f32 v[12:13], v[20:21], v[10:11] op_sel_hi:[0,1]
	v_lshl_add_u64 v[18:19], v[142:143], 1, v[18:19]
	v_cvt_pk_bf16_f32 v10, v14, v15
	v_cvt_pk_bf16_f32 v11, v16, v17
	v_cvt_pk_bf16_f32 v12, v12, v13
	v_cvt_pk_bf16_f32 v13, v22, v23
	flat_store_dwordx4 v[18:19], v[10:13]
	s_and_saveexec_b64 s[2:3], s[0:1]
	s_cbranch_execz .LBB0_144
	v_lshl_add_u64 v[10:11], s[24:25], 0, v[0:1]
	v_mov_b32_e32 v123, v1
	v_lshl_add_u64 v[14:15], v[122:123], 3, v[10:11]
	s_nop 0
	v_mov_b32_e32 v10, v216
	v_mov_b32_e32 v11, v217
	v_mov_b32_e32 v12, v218
	v_mov_b32_e32 v13, v219
	v_mov_b32_e32 v14, v220
	v_mov_b32_e32 v15, v221
	v_mov_b32_e32 v16, v222
	v_mov_b32_e32 v17, v223
	v_pk_mul_f32 v[24:25], v[6:7], v[10:11] op_sel:[1,1] op_sel_hi:[1,0]
	v_mul_f32_e32 v0, v9, v13
	v_pk_mul_f32 v[22:23], v[6:7], v[10:11]
	v_pk_fma_f32 v[6:7], v[6:7], v[10:11], v[24:25] op_sel_hi:[0,1,1]
	v_pk_fma_f32 v[10:11], v[8:9], v[12:13], v[0:1] op_sel_hi:[1,1,0] neg_lo:[0,0,1] neg_hi:[0,0,1]
	v_mul_f32_e32 v0, v9, v12
	v_pk_fma_f32 v[12:13], v[8:9], v[12:13], v[0:1] op_sel:[0,1,0] op_sel_hi:[1,0,0]
	v_pk_mul_f32 v[26:27], v[2:3], v[14:15] op_sel:[1,1] op_sel_hi:[1,0]
	v_mul_f32_e32 v0, v5, v17
	v_pk_mul_f32 v[8:9], v[2:3], v[14:15]
	v_pk_fma_f32 v[2:3], v[2:3], v[14:15], v[26:27] op_sel_hi:[0,1,1]
	v_pk_fma_f32 v[14:15], v[4:5], v[16:17], v[0:1] op_sel_hi:[1,1,0] neg_lo:[0,0,1] neg_hi:[0,0,1]
	v_mul_f32_e32 v0, v5, v16
	v_pk_fma_f32 v[16:17], v[4:5], v[16:17], v[0:1] op_sel:[0,1,0] op_sel_hi:[1,0,0]
	v_sub_f32_e32 v6, v22, v24
	v_sub_f32_e32 v2, v8, v26
	v_mov_b32_e32 v8, v10
	v_mov_b32_e32 v9, v12
	v_mov_b32_e32 v4, v14
	v_mov_b32_e32 v5, v16
.LBB0_144:
	s_or_b64 exec, exec, s[2:3]
	v_mov_b32_e32 v21, v20
	v_mov_b32_e32 v10, v20
	v_mov_b32_e32 v11, v20
	v_pk_mul_f32 v[8:9], v[10:11], v[8:9]
	v_pk_mul_f32 v[6:7], v[20:21], v[6:7]
	v_pk_mul_f32 v[10:11], v[10:11], v[4:5]
	v_pk_mul_f32 v[4:5], v[20:21], v[2:3]
	v_cvt_pk_bf16_f32 v2, v6, v7
	v_cvt_pk_bf16_f32 v3, v8, v9
	v_cvt_pk_bf16_f32 v4, v4, v5
	v_cvt_pk_bf16_f32 v5, v10, v11
	s_andn2_b64 vcc, exec, s[34:35]
	s_mov_b64 s[0:1], -1
	flat_store_dwordx4 v[18:19], v[2:5] offset:256
	s_cbranch_vccnz .LBB0_105
	s_andn2_b64 vcc, exec, s[12:13]
	s_cbranch_vccnz .LBB0_104
	s_barrier
	s_branch .LBB0_104
	s_nop 0
	s_nop 0
	s_nop 0
	s_nop 0
	s_nop 0
	s_nop 0
	s_nop 0
	s_nop 0
	s_nop 0
	s_nop 0
	s_nop 0
	s_nop 0
	s_nop 0
	s_nop 0
	s_nop 0
	s_nop 0
	s_nop 0
	s_nop 0
	s_nop 0
	s_nop 0
	s_nop 0
	s_nop 0
	s_nop 0
	s_nop 0
	s_nop 0
	s_nop 0
	s_nop 0
	s_nop 0
	s_nop 0
	s_nop 0
	s_nop 0
	s_nop 0
	s_nop 0
	s_nop 0
	s_nop 0
	s_nop 0
	s_nop 0
	s_nop 0
	s_nop 0
	s_nop 0
	s_nop 0
	s_nop 0
	s_nop 0
	s_nop 0
	s_nop 0
	s_nop 0
	s_nop 0
	s_nop 0
	s_nop 0
	s_nop 0
	s_nop 0
	s_nop 0
	s_nop 0
	s_nop 0
	s_nop 0
	s_nop 0
	s_nop 0
	s_nop 0

; __device__ __forceinline__ unsigned pk2(float lo, float hi) { f32x2 v = {lo, hi}; bf16x2_t b = __builtin_convertvector(v, bf16x2_t); return __builtin_bit_cast(unsigned, b); }
;     __device__ __forceinline__ void operator()(AccT& acc, const Unit& u, int wr, int wc, int fr, int fq) const {
;         const int row0 = u.pm * BM + wr * 64 + fr; const int cc = wc * 4 + fq;
; #pragma unroll
;         for (int ai = 0; ai < 2; ++ai)
; #pragma unroll
;             for (int m = 0; m < 4; ++m) { const int row = row0 + ai * HALF + m * 16; const float r = rs[row];
;                 const int b = row >> 12, tile = (row >> 6) & 63, key = row & 63;
; #pragma unroll
;                 for (int bj = 0; bj < 2; ++bj) { const f32x4 v0 = acc[ai][bj][m][0] * r, v1 = acc[ai][bj][m][1] * r; const int h = u.pn * 2 + bj;
;                     u32x4 w; w.x = pk2(v0[0], v0[1]); w.y = pk2(v0[2], v0[3]); w.z = pk2(v1[0], v1[1]); w.w = pk2(v1[2], v1[3]);
;                     *(u32x4*)(O + ((size_t)((b * NH + h) * 64 + tile) * 1024 + (key * 16 + (cc ^ (key & 15)))) * 8) = w; } }
.LBB0_168:
	s_lshl_b32 s2, s8, 8
	s_add_i32 s2, s2, s22
	v_or_b32_e32 v144, s2, v146
	v_ashrrev_i32_e32 v145, 31, v144
	v_lshl_add_u64 v[142:143], v[144:145], 2, s[0:1]
	flat_load_dword v150, v[142:143]
	flat_load_dword v162, v[142:143] offset:64
	flat_load_dword v164, v[142:143] offset:128
	flat_load_dword v166, v[142:143] offset:192
	flat_load_dword v168, v[142:143] offset:512
	flat_load_dword v170, v[142:143] offset:576
	flat_load_dword v172, v[142:143] offset:640
	flat_load_dword v174, v[142:143] offset:704
	s_bfe_u32 s3, s2, 0x60006
	s_ashr_i32 s2, s2, 8
	s_lshl_b32 s21, s9, 1
	s_and_b32 s2, s2, 0x3fffff0
	s_add_i32 s2, s2, s21
	s_lshl_b32 s2, s2, 6
	s_or_b32 s2, s2, s3
	s_ashr_i32 s3, s2, 31
	s_lshl_b64 s[8:9], s[2:3], 14
	s_add_u32 s8, s16, s8
	s_addc_u32 s9, s17, s9
	s_or_b32 s2, s2, 64
	s_ashr_i32 s3, s2, 31
	s_lshl_b64 s[2:3], s[2:3], 14
	s_add_u32 s2, s16, s2
	s_addc_u32 s3, s17, s3
	s_movk_i32 s10, 0x1f0
	s_movk_i32 s11, 0x2f0
	s_movk_i32 s25, 0x3f0
	s_andn2_b64 vcc, exec, s[30:31]
	s_waitcnt vmcnt(0) lgkmcnt(0)
	v_pk_mul_f32 v[128:129], v[128:129], v[150:151] op_sel_hi:[1,0]
	v_pk_mul_f32 v[126:127], v[126:127], v[150:151] op_sel_hi:[1,0]
	v_pk_mul_f32 v[152:153], v[124:125], v[150:151] op_sel_hi:[1,0]
	v_pk_mul_f32 v[124:125], v[122:123], v[150:151] op_sel_hi:[1,0]
	v_cvt_pk_bf16_f32 v122, v126, v127
	v_cvt_pk_bf16_f32 v123, v128, v129
	v_cvt_pk_bf16_f32 v124, v124, v125
	v_cvt_pk_bf16_f32 v125, v152, v153
	v_lshl_add_u64 v[126:127], s[8:9], 0, v[0:1]
	flat_store_dwordx4 v[126:127], v[122:125]
	v_pk_mul_f32 v[120:121], v[120:121], v[150:151] op_sel_hi:[1,0]
	v_pk_mul_f32 v[118:119], v[118:119], v[150:151] op_sel_hi:[1,0]
	v_pk_mul_f32 v[122:123], v[116:117], v[150:151] op_sel_hi:[1,0]
	v_pk_mul_f32 v[116:117], v[114:115], v[150:151] op_sel_hi:[1,0]
	v_cvt_pk_bf16_f32 v114, v118, v119
	v_cvt_pk_bf16_f32 v115, v120, v121
	v_cvt_pk_bf16_f32 v116, v116, v117
	v_cvt_pk_bf16_f32 v117, v122, v123
	v_lshl_add_u64 v[118:119], s[2:3], 0, v[0:1]
	flat_store_dwordx4 v[118:119], v[114:117]
	s_nop 1
	v_or_b32_e32 v114, 16, v144
	v_ashrrev_i32_e32 v115, 31, v114
	v_lshl_add_u64 v[116:117], v[114:115], 2, s[0:1]
	s_nop 0
	v_lshlrev_b32_e32 v114, 4, v114
	v_and_or_b32 v117, v114, s10, v148
	v_pk_mul_f32 v[110:111], v[110:111], v[162:163] op_sel_hi:[1,0]
	v_pk_mul_f32 v[112:113], v[112:113], v[162:163] op_sel_hi:[1,0]
	v_pk_mul_f32 v[114:115], v[108:109], v[162:163] op_sel_hi:[1,0]
	v_pk_mul_f32 v[108:109], v[106:107], v[162:163] op_sel_hi:[1,0]
	v_cvt_pk_bf16_f32 v106, v110, v111
	v_lshlrev_b32_e32 v110, 4, v117
	v_mov_b32_e32 v111, v1
	v_cvt_pk_bf16_f32 v107, v112, v113
	v_cvt_pk_bf16_f32 v108, v108, v109
	v_cvt_pk_bf16_f32 v109, v114, v115
	v_lshl_add_u64 v[112:113], s[8:9], 0, v[110:111]
	flat_store_dwordx4 v[112:113], v[106:109]
	v_pk_mul_f32 v[104:105], v[104:105], v[162:163] op_sel_hi:[1,0]
	v_pk_mul_f32 v[102:103], v[102:103], v[162:163] op_sel_hi:[1,0]
	v_pk_mul_f32 v[106:107], v[100:101], v[162:163] op_sel_hi:[1,0]
	v_pk_mul_f32 v[100:101], v[98:99], v[162:163] op_sel_hi:[1,0]
	v_cvt_pk_bf16_f32 v98, v102, v103
	v_cvt_pk_bf16_f32 v99, v104, v105
	v_cvt_pk_bf16_f32 v100, v100, v101
	v_cvt_pk_bf16_f32 v101, v106, v107
	v_lshl_add_u64 v[102:103], s[2:3], 0, v[110:111]
	flat_store_dwordx4 v[102:103], v[98:101]
	s_nop 1
	v_or_b32_e32 v98, 32, v144
	v_ashrrev_i32_e32 v99, 31, v98
	v_lshl_add_u64 v[100:101], v[98:99], 2, s[0:1]
	s_nop 0
	v_lshlrev_b32_e32 v98, 4, v98
	v_and_or_b32 v101, v98, s11, v148
	v_pk_mul_f32 v[94:95], v[94:95], v[164:165] op_sel_hi:[1,0]
	v_pk_mul_f32 v[96:97], v[96:97], v[164:165] op_sel_hi:[1,0]
	v_pk_mul_f32 v[98:99], v[92:93], v[164:165] op_sel_hi:[1,0]
	v_pk_mul_f32 v[92:93], v[90:91], v[164:165] op_sel_hi:[1,0]
	v_cvt_pk_bf16_f32 v90, v94, v95
	v_lshlrev_b32_e32 v94, 4, v101
	v_mov_b32_e32 v95, v1
	v_cvt_pk_bf16_f32 v91, v96, v97
	v_cvt_pk_bf16_f32 v92, v92, v93
	v_cvt_pk_bf16_f32 v93, v98, v99
	v_lshl_add_u64 v[96:97], s[8:9], 0, v[94:95]
	flat_store_dwordx4 v[96:97], v[90:93]
	v_pk_mul_f32 v[88:89], v[88:89], v[164:165] op_sel_hi:[1,0]
	v_pk_mul_f32 v[86:87], v[86:87], v[164:165] op_sel_hi:[1,0]
	v_pk_mul_f32 v[90:91], v[84:85], v[164:165] op_sel_hi:[1,0]
	v_pk_mul_f32 v[84:85], v[82:83], v[164:165] op_sel_hi:[1,0]
	v_cvt_pk_bf16_f32 v82, v86, v87
	v_cvt_pk_bf16_f32 v83, v88, v89
	v_cvt_pk_bf16_f32 v84, v84, v85
	v_cvt_pk_bf16_f32 v85, v90, v91
	v_lshl_add_u64 v[86:87], s[2:3], 0, v[94:95]
	flat_store_dwordx4 v[86:87], v[82:85]
	s_nop 1
	v_or_b32_e32 v82, 48, v144
	v_ashrrev_i32_e32 v83, 31, v82
	v_lshl_add_u64 v[84:85], v[82:83], 2, s[0:1]
	s_nop 0
	v_lshlrev_b32_e32 v82, 4, v82
	v_and_or_b32 v85, v82, s25, v148
	v_pk_mul_f32 v[78:79], v[78:79], v[166:167] op_sel_hi:[1,0]
	v_pk_mul_f32 v[80:81], v[80:81], v[166:167] op_sel_hi:[1,0]
	v_pk_mul_f32 v[82:83], v[76:77], v[166:167] op_sel_hi:[1,0]
	v_pk_mul_f32 v[76:77], v[74:75], v[166:167] op_sel_hi:[1,0]
	v_cvt_pk_bf16_f32 v74, v78, v79
	v_lshlrev_b32_e32 v78, 4, v85
	v_mov_b32_e32 v79, v1
	v_cvt_pk_bf16_f32 v75, v80, v81
	v_cvt_pk_bf16_f32 v76, v76, v77
	v_cvt_pk_bf16_f32 v77, v82, v83
	v_lshl_add_u64 v[80:81], s[8:9], 0, v[78:79]
	flat_store_dwordx4 v[80:81], v[74:77]
; __device__ __forceinline__ unsigned pk2(float lo, float hi) { f32x2 v = {lo, hi}; bf16x2_t b = __builtin_convertvector(v, bf16x2_t); return __builtin_bit_cast(unsigned, b); }
;     __device__ __forceinline__ void operator()(AccT& acc, const Unit& u, int wr, int wc, int fr, int fq) const {
;     ...
;             for (int m = 0; m < 4; ++m) { const int row = row0 + ai * HALF + m * 16; const float r = rs[row];
;                 const int b = row >> 12, tile = (row >> 6) & 63, key = row & 63;
; #pragma unroll
;                 for (int bj = 0; bj < 2; ++bj) { const f32x4 v0 = acc[ai][bj][m][0] * r, v1 = acc[ai][bj][m][1] * r; const int h = u.pn * 2 + bj;
;                     u32x4 w; w.x = pk2(v0[0], v0[1]); w.y = pk2(v0[2], v0[3]); w.z = pk2(v1[0], v1[1]); w.w = pk2(v1[2], v1[3]);
;                     *(u32x4*)(O + ((size_t)((b * NH + h) * 64 + tile) * 1024 + (key * 16 + (cc ^ (key & 15)))) * 8) = w; } }
	v_pk_mul_f32 v[72:73], v[72:73], v[166:167] op_sel_hi:[1,0]
	v_pk_mul_f32 v[70:71], v[70:71], v[166:167] op_sel_hi:[1,0]
	v_pk_mul_f32 v[74:75], v[68:69], v[166:167] op_sel_hi:[1,0]
	v_pk_mul_f32 v[68:69], v[66:67], v[166:167] op_sel_hi:[1,0]
	v_cvt_pk_bf16_f32 v66, v70, v71
	v_cvt_pk_bf16_f32 v67, v72, v73
	v_cvt_pk_bf16_f32 v68, v68, v69
	v_cvt_pk_bf16_f32 v69, v74, v75
	v_lshl_add_u64 v[70:71], s[2:3], 0, v[78:79]
	flat_store_dwordx4 v[70:71], v[66:69]
	s_mov_b64 s[2:3], -1
	s_nop 0
	v_add_u32_e32 v66, 0x80, v144
	v_bfe_u32 v67, v66, 6, 6
	v_ashrrev_i32_e32 v66, 8, v66
	v_and_b32_e32 v66, 0x3fffff0, v66
	v_add_u32_e32 v70, s21, v66
	s_nop 0
	v_pk_mul_f32 v[64:65], v[64:65], v[168:169] op_sel_hi:[1,0]
	v_pk_mul_f32 v[68:69], v[60:61], v[168:169] op_sel_hi:[1,0]
	v_cvt_pk_bf16_f32 v61, v64, v65
	v_lshl_or_b32 v64, v70, 6, v67
	v_pk_mul_f32 v[62:63], v[62:63], v[168:169] op_sel_hi:[1,0]
	v_pk_mul_f32 v[58:59], v[58:59], v[168:169] op_sel_hi:[1,0]
	v_ashrrev_i32_e32 v65, 31, v64
	v_cvt_pk_bf16_f32 v60, v62, v63
	v_cvt_pk_bf16_f32 v62, v58, v59
	v_lshlrev_b64 v[58:59], 14, v[64:65]
	v_lshl_add_u64 v[58:59], s[16:17], 0, v[58:59]
	v_cvt_pk_bf16_f32 v63, v68, v69
	v_lshl_add_u64 v[68:69], v[58:59], 0, v[0:1]
	v_pk_mul_f32 v[54:55], v[54:55], v[168:169] op_sel_hi:[1,0]
	v_pk_mul_f32 v[50:51], v[50:51], v[168:169] op_sel_hi:[1,0]
	flat_store_dwordx4 v[68:69], v[60:63]
	v_pk_mul_f32 v[56:57], v[56:57], v[168:169] op_sel_hi:[1,0]
	s_nop 0
	v_pk_mul_f32 v[60:61], v[52:53], v[168:169] op_sel_hi:[1,0]
	v_cvt_pk_bf16_f32 v52, v54, v55
	v_cvt_pk_bf16_f32 v54, v50, v51
	v_or_b32_e32 v50, 64, v64
	v_ashrrev_i32_e32 v51, 31, v50
	v_lshlrev_b64 v[50:51], 14, v[50:51]
	v_lshl_add_u64 v[50:51], s[16:17], 0, v[50:51]
	v_cvt_pk_bf16_f32 v53, v56, v57
	v_cvt_pk_bf16_f32 v55, v60, v61
	v_lshl_add_u64 v[56:57], v[50:51], 0, v[0:1]
	flat_store_dwordx4 v[56:57], v[52:55]
	s_nop 0
	s_nop 0
	v_lshlrev_b32_e32 v53, 4, v144
	v_add_u32_e32 v54, 0x900, v53
	v_and_or_b32 v56, v54, s10, v148
	v_pk_mul_f32 v[46:47], v[46:47], v[170:171] op_sel_hi:[1,0]
	v_pk_mul_f32 v[48:49], v[48:49], v[170:171] op_sel_hi:[1,0]
	v_pk_mul_f32 v[54:55], v[44:45], v[170:171] op_sel_hi:[1,0]
	v_pk_mul_f32 v[44:45], v[42:43], v[170:171] op_sel_hi:[1,0]
	v_cvt_pk_bf16_f32 v42, v46, v47
	v_lshlrev_b32_e32 v46, 4, v56
	v_mov_b32_e32 v47, v1
	v_cvt_pk_bf16_f32 v43, v48, v49
	v_cvt_pk_bf16_f32 v44, v44, v45
	v_cvt_pk_bf16_f32 v45, v54, v55
	v_lshl_add_u64 v[48:49], v[58:59], 0, v[46:47]
	flat_store_dwordx4 v[48:49], v[42:45]
	v_pk_mul_f32 v[40:41], v[40:41], v[170:171] op_sel_hi:[1,0]
	v_pk_mul_f32 v[38:39], v[38:39], v[170:171] op_sel_hi:[1,0]
	v_pk_mul_f32 v[42:43], v[36:37], v[170:171] op_sel_hi:[1,0]
	v_pk_mul_f32 v[36:37], v[34:35], v[170:171] op_sel_hi:[1,0]
	v_cvt_pk_bf16_f32 v34, v38, v39
	v_cvt_pk_bf16_f32 v35, v40, v41
	v_cvt_pk_bf16_f32 v36, v36, v37
	v_cvt_pk_bf16_f32 v37, v42, v43
	v_lshl_add_u64 v[38:39], v[50:51], 0, v[46:47]
	flat_store_dwordx4 v[38:39], v[34:37]
	s_nop 0
	s_nop 0
	v_add_u32_e32 v35, 0xa00, v53
	v_and_or_b32 v35, v35, s11, v148
	v_pk_mul_f32 v[30:31], v[30:31], v[172:173] op_sel_hi:[1,0]
	v_pk_mul_f32 v[32:33], v[32:33], v[172:173] op_sel_hi:[1,0]
	v_pk_mul_f32 v[36:37], v[28:29], v[172:173] op_sel_hi:[1,0]
	v_pk_mul_f32 v[28:29], v[26:27], v[172:173] op_sel_hi:[1,0]
	v_cvt_pk_bf16_f32 v26, v30, v31
	v_lshlrev_b32_e32 v30, 4, v35
	v_mov_b32_e32 v31, v1
	v_cvt_pk_bf16_f32 v27, v32, v33
	v_cvt_pk_bf16_f32 v28, v28, v29
	v_cvt_pk_bf16_f32 v29, v36, v37
	v_lshl_add_u64 v[32:33], v[58:59], 0, v[30:31]
	flat_store_dwordx4 v[32:33], v[26:29]
	v_pk_mul_f32 v[24:25], v[24:25], v[172:173] op_sel_hi:[1,0]
	v_pk_mul_f32 v[22:23], v[22:23], v[172:173] op_sel_hi:[1,0]
	v_pk_mul_f32 v[26:27], v[20:21], v[172:173] op_sel_hi:[1,0]
	v_pk_mul_f32 v[20:21], v[18:19], v[172:173] op_sel_hi:[1,0]
	v_cvt_pk_bf16_f32 v18, v22, v23
	v_cvt_pk_bf16_f32 v19, v24, v25
	v_cvt_pk_bf16_f32 v20, v20, v21
	v_cvt_pk_bf16_f32 v21, v26, v27
	v_lshl_add_u64 v[22:23], v[50:51], 0, v[30:31]
	flat_store_dwordx4 v[22:23], v[18:21]
	s_nop 0
	s_nop 0
	v_add_u32_e32 v19, 0xb00, v53
	v_and_or_b32 v19, v19, s25, v148
	v_pk_mul_f32 v[14:15], v[14:15], v[174:175] op_sel_hi:[1,0]
	v_pk_mul_f32 v[16:17], v[16:17], v[174:175] op_sel_hi:[1,0]
	v_pk_mul_f32 v[20:21], v[12:13], v[174:175] op_sel_hi:[1,0]
	v_pk_mul_f32 v[12:13], v[10:11], v[174:175] op_sel_hi:[1,0]
	v_cvt_pk_bf16_f32 v10, v14, v15
	v_lshlrev_b32_e32 v14, 4, v19
	v_mov_b32_e32 v15, v1
	v_cvt_pk_bf16_f32 v11, v16, v17
	v_cvt_pk_bf16_f32 v12, v12, v13
	v_cvt_pk_bf16_f32 v13, v20, v21
	v_lshl_add_u64 v[16:17], v[58:59], 0, v[14:15]
	flat_store_dwordx4 v[16:17], v[10:13]
	v_pk_mul_f32 v[8:9], v[8:9], v[174:175] op_sel_hi:[1,0]
	v_pk_mul_f32 v[6:7], v[6:7], v[174:175] op_sel_hi:[1,0]
	v_pk_mul_f32 v[10:11], v[4:5], v[174:175] op_sel_hi:[1,0]
	v_pk_mul_f32 v[4:5], v[2:3], v[174:175] op_sel_hi:[1,0]
	v_cvt_pk_bf16_f32 v2, v6, v7
	v_cvt_pk_bf16_f32 v3, v8, v9
	v_cvt_pk_bf16_f32 v4, v4, v5
	v_cvt_pk_bf16_f32 v5, v10, v11
	v_lshl_add_u64 v[6:7], v[50:51], 0, v[14:15]
	flat_store_dwordx4 v[6:7], v[2:5]
	s_cbranch_vccnz .LBB0_157
	s_andn2_b64 vcc, exec, s[4:5]
	s_cbranch_vccnz .LBB0_156
	s_barrier
	s_branch .LBB0_156

; __global__ void __launch_bounds__(NTHREADS, 2) fwd_kernel(Args A_) {
	.amdhsa_kernel _Z10fwd_kernel4Args
		.amdhsa_group_segment_fixed_size 0
		.amdhsa_private_segment_fixed_size 0
		.amdhsa_kernarg_size 416
		.amdhsa_user_sgpr_count 2
		.amdhsa_user_sgpr_dispatch_ptr 0
		.amdhsa_user_sgpr_queue_ptr 0
		.amdhsa_user_sgpr_kernarg_segment_ptr 1
		.amdhsa_user_sgpr_dispatch_id 0
		.amdhsa_user_sgpr_kernarg_preload_length 0
		.amdhsa_user_sgpr_kernarg_preload_offset 0
		.amdhsa_user_sgpr_private_segment_size 0
		.amdhsa_uses_dynamic_stack 0
		.amdhsa_enable_private_segment 0
		.amdhsa_system_sgpr_workgroup_id_x 1
		.amdhsa_system_sgpr_workgroup_id_y 0
		.amdhsa_system_sgpr_workgroup_id_z 0
		.amdhsa_system_sgpr_workgroup_info 0
		.amdhsa_system_vgpr_workitem_id 2
		.amdhsa_next_free_vgpr 256
		.amdhsa_next_free_sgpr 102
		.amdhsa_accum_offset 256
		.amdhsa_reserve_vcc 1
		.amdhsa_float_round_mode_32 0
		.amdhsa_float_round_mode_16_64 0
		.amdhsa_float_denorm_mode_32 3
		.amdhsa_float_denorm_mode_16_64 3
		.amdhsa_dx10_clamp 1
		.amdhsa_ieee_mode 1
		.amdhsa_fp16_overflow 0
		.amdhsa_tg_split 0
		.amdhsa_exception_fp_ieee_invalid_op 0
		.amdhsa_exception_fp_denorm_src 0
		.amdhsa_exception_fp_ieee_div_zero 0
		.amdhsa_exception_fp_ieee_overflow 0
		.amdhsa_exception_fp_ieee_underflow 0
		.amdhsa_exception_fp_ieee_inexact 0
		.amdhsa_exception_int_div_zero 0
	.end_amdhsa_kernel

; __global__ void __launch_bounds__(NTHREADS, 2) fwd_kernel(Args A_) {
amdhsa.kernels:
  - .agpr_count:     0
    .args:
      - .offset:         0
        .size:           160
        .value_kind:     by_value
      - .offset:         160
        .size:           4
        .value_kind:     hidden_block_count_x
      - .offset:         164
        .size:           4
        .value_kind:     hidden_block_count_y
      - .offset:         168
        .size:           4
        .value_kind:     hidden_block_count_z
      - .offset:         172
        .size:           2
        .value_kind:     hidden_group_size_x
      - .offset:         174
        .size:           2
        .value_kind:     hidden_group_size_y
      - .offset:         176
        .size:           2
        .value_kind:     hidden_group_size_z
      - .offset:         178
        .size:           2
        .value_kind:     hidden_remainder_x
      - .offset:         180
        .size:           2
        .value_kind:     hidden_remainder_y
      - .offset:         182
        .size:           2
        .value_kind:     hidden_remainder_z
      - .offset:         200
        .size:           8
        .value_kind:     hidden_global_offset_x
      - .offset:         208
        .size:           8
        .value_kind:     hidden_global_offset_y
      - .offset:         216
        .size:           8
        .value_kind:     hidden_global_offset_z
      - .offset:         224
        .size:           2
        .value_kind:     hidden_grid_dims
      - .offset:         248
        .size:           8
        .value_kind:     hidden_multigrid_sync_arg
      - .offset:         280
        .size:           4
        .value_kind:     hidden_dynamic_lds_size
    .group_segment_fixed_size: 0
    .kernarg_segment_align: 8
    .kernarg_segment_size: 416
    .language:       OpenCL C
    .language_version:
      - 2
      - 0
    .max_flat_workgroup_size: 512
    .name:           _Z10fwd_kernel4Args
    .private_segment_fixed_size: 0
    .sgpr_count:     108
    .sgpr_spill_count: 199
    .symbol:         _Z10fwd_kernel4Args.kd
    .uniform_work_group_size: 1
    .uses_dynamic_stack: false
    .vgpr_count:     256
    .vgpr_spill_count: 0
    .wavefront_size: 64
